# gates second column tile split by rows between SIMD partner waves (w: mt0-1, w+4: mt2-3) so waves 4-7 no longer idle; hazards re-padded
# speedup vs baseline: 1.0209x; 1.0071x over previous
; DI void phase_rglru(const Params& p, unsigned char* shm) {
;     ...
;         const int chb = w < 4 ? 32 * w : 128 + 16 * (w - 4);
;         {
; #pragma unroll
;           for (int nt = 0; nt < 4; ++nt)
; #pragma unroll
;               for (int kk = 0; kk < 6; ++kk) {
;                   const int chn = chb + ((w < 4) ? 16 * (nt & 1) : 0) + fr;
;                   Bf[nt][kk] = *(const bf16x8*)(WG2 + ((size_t)((blk * 2 + (nt >> 1)) * 192 + chn) * 192 + 32 * kk + 8 * fq)); } }
;         int goff[3], loff[3];
; #pragma unroll
;         for (int j = 0; j < 3; ++j) { const int q = tid + 512 * j, row = q / 24, cc = q % 24; goff[j] = row * 1536 + cc * 8; loff[j] = row * TR + cc * 16; }
;         const size_t base = (size_t)b * S_ * 1536 + cg0;
;         u32x4 rx[3], rg[3];
; #pragma unroll
;         for (int j = 0; j < 3; ++j) { rx[j] = *(const u32x4*)(XRg + base + goff[j]); rg[j] = *(const u32x4*)(Gg + base + goff[j]); }
;     ...
;                     const int ch = chb + 16 * u + fr;
;                     const float ba = gb[ch], bx = gb[192 + ch], sp = gb[384 + ch];
.LBB0_814:
	v_mov_b32_e32 v154, v192
	s_and_b64 vcc, exec, s[40:41]
	v_readfirstlane_b32 s0, v154
	s_cbranch_vccnz .LBB0_854
	v_mul_hi_i32 v2, v154, s71
	v_lshrrev_b32_e32 v3, 31, v2
	v_ashrrev_i32_e32 v2, 2, v2
	s_movk_i32 s1, 0x3c0
	v_add_u32_e32 v2, v2, v3
	s_ashr_i32 s0, s0, 6
	v_cmp_gt_i32_e64 s[42:43], s1, v154
	s_movk_i32 s1, 0x240
	v_mul_lo_u32 v4, v2, 24
	v_cmp_gt_i32_e64 s[44:45], s1, v154
	v_mul_lo_u32 v3, v2, s72
	v_sub_u32_e32 v4, v154, v4
	s_lshl_b32 s1, s0, 4
	v_mul_lo_u32 v2, v2, s73
	v_add_u32_e32 v155, 0x200, v154
	s_lshl_b32 s2, s0, 5
	s_add_i32 s3, s1, 64
	v_lshl_add_u32 v158, v4, 3, v2
	v_mul_hi_i32 v2, v155, s71
	s_cmp_lt_i32 s0, 4
	v_lshrrev_b32_e32 v9, 31, v2
	v_ashrrev_i32_e32 v2, 2, v2
	s_cselect_b64 s[12:13], -1, 0
	v_add_u32_e32 v2, v2, v9
	s_and_b64 s[0:1], s[12:13], exec
	v_mul_lo_u32 v9, v2, 24
	v_and_b32_e32 v0, 15, v154
	s_cselect_b32 s0, s2, s3
	v_sub_u32_e32 v9, v155, v9
	v_mul_lo_u32 v10, v2, s73
	v_bfe_u32 v1, v154, 4, 2
	v_or_b32_e32 v175, s0, v0
	v_readlane_b32 s0, v244, 18
	v_lshl_add_u32 v160, v9, 3, v10
	v_add_u32_e32 v10, 0x400, v154
	v_lshlrev_b32_e32 v152, 4, v1
	v_readlane_b32 s1, v244, 19
	v_mul_hi_i32 v11, v10, s71
	v_lshrrev_b32_e32 v12, 31, v11
	v_lshl_add_u64 v[156:157], s[0:1], 0, v[152:153]
	s_movk_i32 s0, 0xbf
	v_ashrrev_i32_e32 v11, 2, v11
	v_cmp_lt_i32_e64 s[48:49], s0, v154
	v_add_u32_e32 v7, 0xffffff00, v154
	s_movk_i32 s0, 0xab
	v_add_u32_e32 v11, v11, v12
	v_max_i32_e32 v15, 64, v154
	v_max_i32_e32 v17, 0x1c0, v154
	v_lshlrev_b32_e32 v5, 4, v4
	v_cmp_gt_u32_e64 s[50:51], s70, v7
	v_mul_lo_u16_sdwa v7, v154, s0 dst_sel:DWORD dst_unused:UNUSED_PAD src0_sel:BYTE_0 src1_sel:DWORD
	v_mul_lo_u32 v12, v11, 24
	v_lshlrev_b32_e32 v4, 5, v4
	v_sub_u32_e32 v15, v15, v154
	v_sub_u32_e32 v17, v17, v154
	v_lshrrev_b16_e32 v7, 12, v7
	v_sub_u32_e32 v10, v10, v12
	v_mul_lo_u32 v12, v11, s73
	v_add_u32_e32 v178, s74, v4
	v_add_u32_e32 v179, s75, v4
	v_lshlrev_b32_e32 v4, 5, v9
	v_add_u32_e32 v15, 0x1ff, v15
	v_add_u32_e32 v17, 0x1ff, v17
	v_mul_lo_u16_e32 v8, 24, v7
	v_lshl_add_u32 v162, v10, 3, v12
	v_add_u32_e32 v180, s74, v4
	v_add_u32_e32 v181, s75, v4
	v_lshlrev_b32_e32 v4, 5, v10
	v_and_b32_e32 v177, 0xfffffff0, v175
	v_add_u32_e32 v177, v177, v175
	v_add_u32_e32 v177, 0xffffff10, v177
	v_add_u32_e32 v12, 16, v175
	v_cndmask_b32_e64 v12, v177, v12, s[12:13]
	v_mov_b32_e32 v177, v12
	v_lshrrev_b32_e32 v16, 9, v15
	v_lshrrev_b32_e32 v18, 9, v17
	v_sub_u16_e32 v8, v154, v8
	s_cselect_b32 s0, 16, 0
	v_mul_lo_u32 v2, v2, s72
	v_mul_lo_u32 v11, v11, s72
	v_add_u32_e32 v182, s74, v4
	v_add_u32_e32 v183, s75, v4
	v_lshlrev_b32_e32 v4, 1, v175
	v_lshl_add_u32 v185, v12, 2, s76
	v_lshlrev_b32_e32 v12, 1, v12
	v_add_u32_e32 v16, 1, v16
	v_add_u32_e32 v18, 1, v18
	v_add_u32_e32 v3, 0, v3
	v_add_u32_e32 v6, 0, v152
	v_mad_u32_u24 v7, v7, s72, 0
	v_lshlrev_b32_sdwa v8, v173, v8 dst_sel:DWORD dst_unused:UNUSED_PAD src0_sel:DWORD src1_sel:BYTE_0
	v_lshl_add_u32 v2, v9, 4, v2
	v_lshl_add_u32 v11, v10, 4, v11
	v_mul_u32_u24_e32 v0, 0x190, v0
	v_add_u32_e32 v9, 0, v4
	v_add_u32_e32 v10, s77, v4
	v_add_u32_e32 v4, s79, v4
	v_mul_u32_u24_e32 v1, 0x640, v1
	v_add_u32_e32 v13, 0, v12
	v_add_u32_e32 v14, s77, v12
	v_add_u32_e32 v12, s79, v12
	v_and_b32_e32 v186, 0xfffffe, v18
	v_and_b32_e32 v188, 0xfffffe, v16
	v_lshlrev_b32_e32 v190, 2, v154
	v_readlane_b32 s0, v246, 35
	v_cmp_gt_i32_e64 s[46:47], s70, v154
	v_lshl_add_u32 v176, v154, 1, 0
	v_ashrrev_i32_e32 v159, 31, v158
	v_ashrrev_i32_e32 v161, 31, v160
	v_ashrrev_i32_e32 v163, 31, v162
	v_lshl_add_u32 v184, v175, 2, s76
	v_cmp_lt_u32_e64 s[52:53], s82, v17
	v_lshl_add_u32 v187, v186, 9, v154
	v_cmp_ne_u32_e64 s[54:55], v18, v186
	v_cmp_lt_u32_e64 s[6:7], s82, v15
	v_lshl_add_u32 v189, v188, 9, v154
	v_cmp_ne_u32_e64 s[4:5], v16, v188
	v_add_u32_e32 v191, s83, v190
	v_add_u32_e32 v193, s86, v190
	v_add_u32_e32 v194, v9, v1
	v_add_u32_e32 v195, v10, v1
	v_add_u32_e32 v196, v4, v1
	v_add_u32_e32 v197, v13, v1
	v_add_u32_e32 v198, v14, v1
	v_add_u32_e32 v199, v12, v1
	v_add_u32_e32 v200, v7, v8
	v_add_u32_e32 v201, v3, v5
	v_add_u32_e32 v202, 0, v2
	v_add_u32_e32 v203, 0, v11
	v_add_u32_e32 v204, v6, v0
	s_mov_b32 s30, s0
	s_mov_b32 s31, s0
	v_readlane_b32 s1, v246, 36
	s_branch .LBB0_817

; #define LAS __attribute__((address_space(3)))
; DI u32x4 pack8f(const float (&f)[8]) { u32x4 r; r[0] = pk2(f[0], f[1]); r[1] = pk2(f[2], f[3]); r[2] = pk2(f[4], f[5]); r[3] = pk2(f[6], f[7]); return r; }
; DI void phase_rglru(const Params& p, unsigned char* shm) {
;     ...
;             for (int j = 0; j < 3; ++j) {
;                 const int q = tid + 512 * j, cc = q % 24;
;                 float a8[8];
;                 { const f32x4 b0 = *(const LAS f32x4*)(cw + 768 + 8 * cc), b1 = *(const LAS f32x4*)(cw + 768 + 8 * cc + 4);
; #pragma unroll
;                   for (int e = 0; e < 4; ++e) { a8[e] = b0[e]; a8[4 + e] = b1[e]; } }
; #pragma unroll
;                 for (int jj = 0; jj < 4; ++jj) {
;                     float xin[8]; { const u32x4 xraw = *(const LAS u32x4*)(lds + XR + jj * TR + loff[j]); unpack8(xraw, xin); }
;                     const f32x4 w0 = *(const LAS f32x4*)(cw + jj * 192 + 8 * cc), w1 = *(const LAS f32x4*)(cw + jj * 192 + 8 * cc + 4);
; #pragma unroll
;                     for (int e = 0; e < 4; ++e) { a8[e] += w0[e] * xin[e]; a8[4 + e] += w1[e] * xin[4 + e]; }
;                 }
;                 *(LAS u32x4*)(lds + XC + loff[j]) = pack8f(a8);
.LBB0_845:
	s_waitcnt lgkmcnt(0)
	s_barrier
	ds_read_b128 v[120:123], v178
	ds_read_b128 v[124:127], v178 offset:16
	ds_read_b128 v[128:131], v201
	ds_read_b128 v[132:135], v179
	ds_read_b128 v[136:139], v179 offset:16
	ds_read_b128 v[140:143], v201 offset:400
	ds_read_b128 v[144:147], v179 offset:768
	ds_read_b128 v[148:151], v179 offset:784
	ds_read_b128 v[210:213], v201 offset:800
	ds_read_b128 v[214:217], v179 offset:1536
	ds_read_b128 v[218:221], v179 offset:1552
	ds_read_b128 v[222:225], v201 offset:1200
	ds_read_b128 v[226:229], v179 offset:2304
	ds_read_b128 v[230:233], v179 offset:2320
	s_waitcnt lgkmcnt(11)
	v_lshlrev_b32_e32 v170, 16, v128
	v_and_b32_e32 v171, 0xffff0000, v128
	v_lshlrev_b32_e32 v128, 16, v129
	v_and_b32_e32 v129, 0xffff0000, v129
	s_waitcnt lgkmcnt(10)
	v_pk_fma_f32 v[120:121], v[132:133], v[170:171], v[120:121]
	s_waitcnt lgkmcnt(8)
	v_lshlrev_b32_e32 v132, 16, v140
	v_and_b32_e32 v133, 0xffff0000, v140
	v_pk_fma_f32 v[122:123], v[134:135], v[128:129], v[122:123]
	v_lshlrev_b32_e32 v128, 16, v141
	v_and_b32_e32 v129, 0xffff0000, v141
	s_waitcnt lgkmcnt(7)
	v_pk_fma_f32 v[120:121], v[144:145], v[132:133], v[120:121]
	s_waitcnt lgkmcnt(5)
	v_lshlrev_b32_e32 v132, 16, v210
	v_and_b32_e32 v133, 0xffff0000, v210
	v_pk_fma_f32 v[122:123], v[146:147], v[128:129], v[122:123]
	v_lshlrev_b32_e32 v128, 16, v211
	v_and_b32_e32 v129, 0xffff0000, v211
	s_waitcnt lgkmcnt(4)
	v_pk_fma_f32 v[120:121], v[214:215], v[132:133], v[120:121]
	s_waitcnt lgkmcnt(2)
	v_lshlrev_b32_e32 v132, 16, v222
	v_and_b32_e32 v133, 0xffff0000, v222
	v_pk_fma_f32 v[122:123], v[216:217], v[128:129], v[122:123]
	v_lshlrev_b32_e32 v128, 16, v223
	v_and_b32_e32 v129, 0xffff0000, v223
	s_waitcnt lgkmcnt(1)
	v_pk_fma_f32 v[120:121], v[226:227], v[132:133], v[120:121]
	v_lshlrev_b32_e32 v132, 16, v130
	v_and_b32_e32 v133, 0xffff0000, v130
	v_pk_fma_f32 v[122:123], v[228:229], v[128:129], v[122:123]
	v_lshlrev_b32_e32 v128, 16, v131
	v_and_b32_e32 v129, 0xffff0000, v131
	v_pk_fma_f32 v[124:125], v[136:137], v[132:133], v[124:125]
	v_lshlrev_b32_e32 v132, 16, v142
	v_and_b32_e32 v133, 0xffff0000, v142
	v_pk_fma_f32 v[126:127], v[138:139], v[128:129], v[126:127]
	v_lshlrev_b32_e32 v128, 16, v143
	v_and_b32_e32 v129, 0xffff0000, v143
	v_pk_fma_f32 v[124:125], v[148:149], v[132:133], v[124:125]
	v_lshlrev_b32_e32 v132, 16, v212
	v_and_b32_e32 v133, 0xffff0000, v212
	v_pk_fma_f32 v[126:127], v[150:151], v[128:129], v[126:127]
	v_lshlrev_b32_e32 v128, 16, v213
	v_and_b32_e32 v129, 0xffff0000, v213
	v_pk_fma_f32 v[124:125], v[218:219], v[132:133], v[124:125]
	v_lshlrev_b32_e32 v132, 16, v224
	v_and_b32_e32 v133, 0xffff0000, v224
	v_pk_fma_f32 v[126:127], v[220:221], v[128:129], v[126:127]
	v_lshlrev_b32_e32 v128, 16, v225
	v_and_b32_e32 v129, 0xffff0000, v225
	s_waitcnt lgkmcnt(0)
	v_pk_fma_f32 v[124:125], v[230:231], v[132:133], v[124:125]
	v_pk_fma_f32 v[126:127], v[232:233], v[128:129], v[126:127]
	v_cvt_pk_bf16_f32 v120, v120, v121
	v_cvt_pk_bf16_f32 v121, v122, v123
	v_cvt_pk_bf16_f32 v122, v124, v125
	v_cvt_pk_bf16_f32 v123, v126, v127
	ds_write_b128 v201, v[120:123] offset:26880
	ds_read_b128 v[120:123], v180
	ds_read_b128 v[124:127], v180 offset:16
	ds_read_b128 v[128:131], v202
	ds_read_b128 v[132:135], v181
	ds_read_b128 v[136:139], v181 offset:16
	ds_read_b128 v[140:143], v202 offset:400
	ds_read_b128 v[144:147], v181 offset:768
	ds_read_b128 v[148:151], v181 offset:784
	ds_read_b128 v[210:213], v202 offset:800
	ds_read_b128 v[214:217], v181 offset:1536
	ds_read_b128 v[218:221], v181 offset:1552
	ds_read_b128 v[222:225], v202 offset:1200
	ds_read_b128 v[226:229], v181 offset:2304
	ds_read_b128 v[230:233], v181 offset:2320
	s_waitcnt lgkmcnt(11)
	v_lshlrev_b32_e32 v170, 16, v128
	v_and_b32_e32 v171, 0xffff0000, v128
	v_lshlrev_b32_e32 v128, 16, v129
	v_and_b32_e32 v129, 0xffff0000, v129
	s_waitcnt lgkmcnt(10)
	v_pk_fma_f32 v[120:121], v[132:133], v[170:171], v[120:121]
	s_waitcnt lgkmcnt(8)
	v_lshlrev_b32_e32 v132, 16, v140
	v_and_b32_e32 v133, 0xffff0000, v140
	v_pk_fma_f32 v[122:123], v[134:135], v[128:129], v[122:123]
	v_lshlrev_b32_e32 v128, 16, v141
	v_and_b32_e32 v129, 0xffff0000, v141
	s_waitcnt lgkmcnt(7)
	v_pk_fma_f32 v[120:121], v[144:145], v[132:133], v[120:121]
	s_waitcnt lgkmcnt(5)
	v_lshlrev_b32_e32 v132, 16, v210
	v_and_b32_e32 v133, 0xffff0000, v210
	v_pk_fma_f32 v[122:123], v[146:147], v[128:129], v[122:123]
	v_lshlrev_b32_e32 v128, 16, v211
	v_and_b32_e32 v129, 0xffff0000, v211
	s_waitcnt lgkmcnt(4)
	v_pk_fma_f32 v[120:121], v[214:215], v[132:133], v[120:121]
	s_waitcnt lgkmcnt(2)
	v_lshlrev_b32_e32 v132, 16, v222
	v_and_b32_e32 v133, 0xffff0000, v222
	v_pk_fma_f32 v[122:123], v[216:217], v[128:129], v[122:123]
	v_lshlrev_b32_e32 v128, 16, v223
	v_and_b32_e32 v129, 0xffff0000, v223
	s_waitcnt lgkmcnt(1)
	v_pk_fma_f32 v[120:121], v[226:227], v[132:133], v[120:121]
	v_lshlrev_b32_e32 v132, 16, v130
	v_and_b32_e32 v133, 0xffff0000, v130
	v_pk_fma_f32 v[122:123], v[228:229], v[128:129], v[122:123]
	v_lshlrev_b32_e32 v128, 16, v131
	v_and_b32_e32 v129, 0xffff0000, v131
	v_pk_fma_f32 v[124:125], v[136:137], v[132:133], v[124:125]
	v_lshlrev_b32_e32 v132, 16, v142
	v_and_b32_e32 v133, 0xffff0000, v142
	v_pk_fma_f32 v[126:127], v[138:139], v[128:129], v[126:127]
	v_lshlrev_b32_e32 v128, 16, v143
	v_and_b32_e32 v129, 0xffff0000, v143
	v_pk_fma_f32 v[124:125], v[148:149], v[132:133], v[124:125]
	v_lshlrev_b32_e32 v132, 16, v212
	v_and_b32_e32 v133, 0xffff0000, v212
	v_pk_fma_f32 v[126:127], v[150:151], v[128:129], v[126:127]
	v_lshlrev_b32_e32 v128, 16, v213
	v_and_b32_e32 v129, 0xffff0000, v213
	v_pk_fma_f32 v[124:125], v[218:219], v[132:133], v[124:125]
	v_lshlrev_b32_e32 v132, 16, v224
	v_and_b32_e32 v133, 0xffff0000, v224
	v_pk_fma_f32 v[126:127], v[220:221], v[128:129], v[126:127]
	v_lshlrev_b32_e32 v128, 16, v225
	v_and_b32_e32 v129, 0xffff0000, v225
	s_waitcnt lgkmcnt(0)
; #define LAS __attribute__((address_space(3)))
; DI u32x4 pack8f(const float (&f)[8]) { u32x4 r; r[0] = pk2(f[0], f[1]); r[1] = pk2(f[2], f[3]); r[2] = pk2(f[4], f[5]); r[3] = pk2(f[6], f[7]); return r; }
; DI void phase_rglru(const Params& p, unsigned char* shm) {
;     ...
;                     float xin[8]; { const u32x4 xraw = *(const LAS u32x4*)(lds + XR + jj * TR + loff[j]); unpack8(xraw, xin); }
;                     const f32x4 w0 = *(const LAS f32x4*)(cw + jj * 192 + 8 * cc), w1 = *(const LAS f32x4*)(cw + jj * 192 + 8 * cc + 4);
; #pragma unroll
;                     for (int e = 0; e < 4; ++e) { a8[e] += w0[e] * xin[e]; a8[4 + e] += w1[e] * xin[4 + e]; }
;                 }
;                 *(LAS u32x4*)(lds + XC + loff[j]) = pack8f(a8);
;             }
;             __syncthreads();
;             {
; #pragma unroll
;                 for (int u = 0; u < 2; ++u) {
;                     if (u == 1 && w >= 4) break;
;                     f32x4 acc[4][2];
; #pragma unroll
;                     for (int mt = 0; mt < 4; ++mt) { acc[mt][0] = (f32x4){0.f, 0.f, 0.f, 0.f}; acc[mt][1] = (f32x4){0.f, 0.f, 0.f, 0.f}; }
; #pragma unroll
;                     for (int kk = 0; kk < 6; ++kk)
; #pragma unroll
;                         for (int mt = 0; mt < 4; ++mt) {
;                             const bf16x8 af = *(const LAS bf16x8*)(lds + XC + (16 * mt + fr) * TR + (32 * kk + 8 * fq) * 2);
;                             acc[mt][0] = __builtin_amdgcn_mfma_f32_16x16x32_bf16(af, Bf[u][kk], acc[mt][0], 0, 0, 0);
;                             acc[mt][1] = __builtin_amdgcn_mfma_f32_16x16x32_bf16(af, Bf[2 + u][kk], acc[mt][1], 0, 0, 0);
;                         }
	v_pk_fma_f32 v[124:125], v[230:231], v[132:133], v[124:125]
	v_pk_fma_f32 v[126:127], v[232:233], v[128:129], v[126:127]
	v_cvt_pk_bf16_f32 v120, v120, v121
	v_cvt_pk_bf16_f32 v121, v122, v123
	v_cvt_pk_bf16_f32 v122, v124, v125
	v_cvt_pk_bf16_f32 v123, v126, v127
	ds_write_b128 v202, v[120:123] offset:26880
	ds_read_b128 v[120:123], v182
	ds_read_b128 v[124:127], v182 offset:16
	ds_read_b128 v[128:131], v203
	ds_read_b128 v[132:135], v183
	ds_read_b128 v[136:139], v183 offset:16
	ds_read_b128 v[140:143], v203 offset:400
	ds_read_b128 v[144:147], v183 offset:768
	ds_read_b128 v[148:151], v183 offset:784
	ds_read_b128 v[210:213], v203 offset:800
	ds_read_b128 v[214:217], v183 offset:1536
	ds_read_b128 v[218:221], v183 offset:1552
	ds_read_b128 v[222:225], v203 offset:1200
	ds_read_b128 v[226:229], v183 offset:2304
	ds_read_b128 v[230:233], v183 offset:2320
	s_waitcnt lgkmcnt(11)
	v_lshlrev_b32_e32 v170, 16, v128
	v_and_b32_e32 v171, 0xffff0000, v128
	v_lshlrev_b32_e32 v128, 16, v129
	v_and_b32_e32 v129, 0xffff0000, v129
	s_waitcnt lgkmcnt(10)
	v_pk_fma_f32 v[120:121], v[132:133], v[170:171], v[120:121]
	s_waitcnt lgkmcnt(8)
	v_lshlrev_b32_e32 v132, 16, v140
	v_and_b32_e32 v133, 0xffff0000, v140
	v_pk_fma_f32 v[122:123], v[134:135], v[128:129], v[122:123]
	v_lshlrev_b32_e32 v128, 16, v141
	v_and_b32_e32 v129, 0xffff0000, v141
	s_waitcnt lgkmcnt(7)
	v_pk_fma_f32 v[120:121], v[144:145], v[132:133], v[120:121]
	s_waitcnt lgkmcnt(5)
	v_lshlrev_b32_e32 v132, 16, v210
	v_and_b32_e32 v133, 0xffff0000, v210
	v_pk_fma_f32 v[122:123], v[146:147], v[128:129], v[122:123]
	v_lshlrev_b32_e32 v128, 16, v211
	v_and_b32_e32 v129, 0xffff0000, v211
	s_waitcnt lgkmcnt(4)
	v_pk_fma_f32 v[120:121], v[214:215], v[132:133], v[120:121]
	s_waitcnt lgkmcnt(2)
	v_lshlrev_b32_e32 v132, 16, v222
	v_and_b32_e32 v133, 0xffff0000, v222
	v_pk_fma_f32 v[122:123], v[216:217], v[128:129], v[122:123]
	v_lshlrev_b32_e32 v128, 16, v223
	v_and_b32_e32 v129, 0xffff0000, v223
	s_waitcnt lgkmcnt(1)
	v_pk_fma_f32 v[120:121], v[226:227], v[132:133], v[120:121]
	v_lshlrev_b32_e32 v132, 16, v130
	v_and_b32_e32 v133, 0xffff0000, v130
	v_pk_fma_f32 v[122:123], v[228:229], v[128:129], v[122:123]
	v_lshlrev_b32_e32 v128, 16, v131
	v_and_b32_e32 v129, 0xffff0000, v131
	v_pk_fma_f32 v[124:125], v[136:137], v[132:133], v[124:125]
	v_lshlrev_b32_e32 v132, 16, v142
	v_and_b32_e32 v133, 0xffff0000, v142
	v_pk_fma_f32 v[126:127], v[138:139], v[128:129], v[126:127]
	v_lshlrev_b32_e32 v128, 16, v143
	v_and_b32_e32 v129, 0xffff0000, v143
	v_pk_fma_f32 v[124:125], v[148:149], v[132:133], v[124:125]
	v_lshlrev_b32_e32 v132, 16, v212
	v_and_b32_e32 v133, 0xffff0000, v212
	v_pk_fma_f32 v[126:127], v[150:151], v[128:129], v[126:127]
	v_lshlrev_b32_e32 v128, 16, v213
	v_and_b32_e32 v129, 0xffff0000, v213
	v_pk_fma_f32 v[124:125], v[218:219], v[132:133], v[124:125]
	v_lshlrev_b32_e32 v132, 16, v224
	v_and_b32_e32 v133, 0xffff0000, v224
	v_pk_fma_f32 v[126:127], v[220:221], v[128:129], v[126:127]
	v_lshlrev_b32_e32 v128, 16, v225
	v_and_b32_e32 v129, 0xffff0000, v225
	s_waitcnt lgkmcnt(0)
	v_pk_fma_f32 v[124:125], v[230:231], v[132:133], v[124:125]
	v_pk_fma_f32 v[126:127], v[232:233], v[128:129], v[126:127]
	v_cvt_pk_bf16_f32 v120, v120, v121
	v_cvt_pk_bf16_f32 v121, v122, v123
	v_cvt_pk_bf16_f32 v122, v124, v125
	v_cvt_pk_bf16_f32 v123, v126, v127
	ds_write_b128 v203, v[120:123] offset:26880
	s_waitcnt lgkmcnt(0)
	s_barrier
	ds_read_b128 v[120:123], v204 offset:26880
	ds_read_b128 v[124:127], v204 offset:33280
	ds_read_b128 v[128:131], v204 offset:39680
	ds_read_b128 v[132:135], v204 offset:46080
	ds_read_b128 v[226:229], v204 offset:26944
	s_waitcnt lgkmcnt(4)
	v_mfma_f32_16x16x32_bf16 v[148:151], v[120:123], v[0:3], 0
	v_mfma_f32_16x16x32_bf16 v[144:147], v[120:123], v[48:51], 0
	ds_read_b128 v[230:233], v204 offset:33344
	s_waitcnt lgkmcnt(4)
	v_mfma_f32_16x16x32_bf16 v[140:143], v[124:127], v[0:3], 0
	v_mfma_f32_16x16x32_bf16 v[136:139], v[124:127], v[48:51], 0
	ds_read_b128 v[120:123], v204 offset:39744
	s_waitcnt lgkmcnt(4)
	v_mfma_f32_16x16x32_bf16 v[214:217], v[128:131], v[0:3], 0
	v_mfma_f32_16x16x32_bf16 v[210:213], v[128:131], v[48:51], 0
	ds_read_b128 v[124:127], v204 offset:46144
	s_waitcnt lgkmcnt(4)
	v_mfma_f32_16x16x32_bf16 v[218:221], v[132:135], v[0:3], 0
	v_mfma_f32_16x16x32_bf16 v[222:225], v[132:135], v[48:51], 0
	ds_read_b128 v[128:131], v204 offset:27008
	s_waitcnt lgkmcnt(4)
	v_mfma_f32_16x16x32_bf16 v[148:151], v[226:229], v[4:7], v[148:151]
	v_mfma_f32_16x16x32_bf16 v[144:147], v[226:229], v[52:55], v[144:147]
	ds_read_b128 v[132:135], v204 offset:33408
	s_waitcnt lgkmcnt(4)
	v_mfma_f32_16x16x32_bf16 v[140:143], v[230:233], v[4:7], v[140:143]
	v_mfma_f32_16x16x32_bf16 v[136:139], v[230:233], v[52:55], v[136:139]
	ds_read_b128 v[226:229], v204 offset:39808
	s_waitcnt lgkmcnt(4)
	v_mfma_f32_16x16x32_bf16 v[214:217], v[120:123], v[4:7], v[214:217]
	v_mfma_f32_16x16x32_bf16 v[210:213], v[120:123], v[52:55], v[210:213]
	ds_read_b128 v[230:233], v204 offset:46208
	s_waitcnt lgkmcnt(4)
	v_mfma_f32_16x16x32_bf16 v[218:221], v[124:127], v[4:7], v[218:221]
	v_mfma_f32_16x16x32_bf16 v[222:225], v[124:127], v[52:55], v[222:225]
	ds_read_b128 v[120:123], v204 offset:27072
	s_waitcnt lgkmcnt(4)
	v_mfma_f32_16x16x32_bf16 v[148:151], v[128:131], v[8:11], v[148:151]
	v_mfma_f32_16x16x32_bf16 v[144:147], v[128:131], v[56:59], v[144:147]
	ds_read_b128 v[124:127], v204 offset:33472
	s_waitcnt lgkmcnt(4)
	v_mfma_f32_16x16x32_bf16 v[140:143], v[132:135], v[8:11], v[140:143]
	v_mfma_f32_16x16x32_bf16 v[136:139], v[132:135], v[56:59], v[136:139]
	ds_read_b128 v[128:131], v204 offset:39872
	s_waitcnt lgkmcnt(4)
; #define LAS __attribute__((address_space(3)))
; DI unsigned pk2(float a, float b) { f32x2 v = {a, b}; bf2_t r = __builtin_convertvector(v, bf2_t); return __builtin_bit_cast(unsigned, r); }
; DI void phase_rglru(const Params& p, unsigned char* shm) {
;     ...
; #pragma unroll
;                     for (int kk = 0; kk < 6; ++kk)
; #pragma unroll
;                         for (int mt = 0; mt < 4; ++mt) {
;                             const bf16x8 af = *(const LAS bf16x8*)(lds + XC + (16 * mt + fr) * TR + (32 * kk + 8 * fq) * 2);
;                             acc[mt][0] = __builtin_amdgcn_mfma_f32_16x16x32_bf16(af, Bf[u][kk], acc[mt][0], 0, 0, 0);
;                             acc[mt][1] = __builtin_amdgcn_mfma_f32_16x16x32_bf16(af, Bf[2 + u][kk], acc[mt][1], 0, 0, 0);
;                         }
;                     const int ch = chb + 16 * u + fr;
;                     const float ba = gb[ch], bx = gb[192 + ch], sp = gb[384 + ch];
; #pragma unroll
;                     for (int mt = 0; mt < 4; ++mt)
; #pragma unroll
;                         for (int j = 0; j < 4; ++j) {
;                             const int t = 16 * mt + 4 * fq + j;
;                             const float ea = 1.f + __expf(fminf(-(acc[mt][0][j] + ba), 40.f)), ex = 1.f + __expf(fminf(-(acc[mt][1][j] + bx), 40.f));
;                             const float inv = __builtin_amdgcn_rcpf(ea * ex);
;                             const float r = inv * ex, ig = inv * ea;
;                             const float av = __expf(r * sp), om = 1.f - av;
;                             const float xcv = __uint_as_float((unsigned)*(const LAS bf16_t*)(lds + XC + t * TR + ch * 2) << 16);
;                             const float bt = __builtin_amdgcn_sqrtf(fmaxf(om * (1.f + av), 0.f)) * (ig * xcv);
;                             *(LAS bf16_t*)(lds + LAo + t * TR + ch * 2) = (bf16_t)(pk2(om, 0.f) & 0xffffu);
;                             *(LAS bf16_t*)(lds + BTo + t * TR + ch * 2) = (bf16_t)(pk2(bt, 0.f) & 0xffffu);
;                         }
	v_mfma_f32_16x16x32_bf16 v[214:217], v[226:229], v[8:11], v[214:217]
	v_mfma_f32_16x16x32_bf16 v[210:213], v[226:229], v[56:59], v[210:213]
	ds_read_b128 v[132:135], v204 offset:46272
	s_waitcnt lgkmcnt(4)
	v_mfma_f32_16x16x32_bf16 v[218:221], v[230:233], v[8:11], v[218:221]
	v_mfma_f32_16x16x32_bf16 v[222:225], v[230:233], v[56:59], v[222:225]
	ds_read_b128 v[226:229], v204 offset:27136
	s_waitcnt lgkmcnt(4)
	v_mfma_f32_16x16x32_bf16 v[148:151], v[120:123], v[12:15], v[148:151]
	v_mfma_f32_16x16x32_bf16 v[144:147], v[120:123], v[60:63], v[144:147]
	ds_read_b128 v[230:233], v204 offset:33536
	s_waitcnt lgkmcnt(4)
	v_mfma_f32_16x16x32_bf16 v[140:143], v[124:127], v[12:15], v[140:143]
	v_mfma_f32_16x16x32_bf16 v[136:139], v[124:127], v[60:63], v[136:139]
	ds_read_b128 v[120:123], v204 offset:39936
	s_waitcnt lgkmcnt(4)
	v_mfma_f32_16x16x32_bf16 v[214:217], v[128:131], v[12:15], v[214:217]
	v_mfma_f32_16x16x32_bf16 v[210:213], v[128:131], v[60:63], v[210:213]
	ds_read_b128 v[124:127], v204 offset:46336
	s_waitcnt lgkmcnt(4)
	v_mfma_f32_16x16x32_bf16 v[218:221], v[132:135], v[12:15], v[218:221]
	v_mfma_f32_16x16x32_bf16 v[222:225], v[132:135], v[60:63], v[222:225]
	ds_read_b128 v[128:131], v204 offset:27200
	s_waitcnt lgkmcnt(4)
	v_mfma_f32_16x16x32_bf16 v[148:151], v[226:229], v[16:19], v[148:151]
	v_mfma_f32_16x16x32_bf16 v[144:147], v[226:229], v[64:67], v[144:147]
	ds_read_b128 v[132:135], v204 offset:33600
	s_waitcnt lgkmcnt(4)
	v_mfma_f32_16x16x32_bf16 v[140:143], v[230:233], v[16:19], v[140:143]
	v_mfma_f32_16x16x32_bf16 v[136:139], v[230:233], v[64:67], v[136:139]
	s_waitcnt lgkmcnt(3)
	v_mfma_f32_16x16x32_bf16 v[214:217], v[120:123], v[16:19], v[214:217]
	v_mfma_f32_16x16x32_bf16 v[210:213], v[120:123], v[64:67], v[210:213]
	s_waitcnt lgkmcnt(2)
	v_mfma_f32_16x16x32_bf16 v[218:221], v[124:127], v[16:19], v[218:221]
	v_mfma_f32_16x16x32_bf16 v[222:225], v[124:127], v[64:67], v[222:225]
	s_waitcnt lgkmcnt(1)
	v_mfma_f32_16x16x32_bf16 v[148:151], v[128:131], v[20:23], v[148:151]
	v_mfma_f32_16x16x32_bf16 v[144:147], v[128:131], v[68:71], v[144:147]
	s_waitcnt lgkmcnt(0)
	v_mfma_f32_16x16x32_bf16 v[140:143], v[132:135], v[20:23], v[140:143]
	v_mfma_f32_16x16x32_bf16 v[136:139], v[132:135], v[68:71], v[136:139]
	ds_read_b128 v[120:123], v204 offset:40000
	s_nop 1
	ds_read_b128 v[128:131], v204 offset:46400
	ds_read2st64_b32 v[170:171], v184 offset1:3
	ds_read_b32 v205, v184 offset:1536
	ds_read_u16 v226, v194 offset:26880
	ds_read_u16 v227, v194 offset:27280
	ds_read_u16 v228, v194 offset:27680
	ds_read_u16 v229, v194 offset:28080
	ds_read_u16 v230, v194 offset:33280
	ds_read_u16 v231, v194 offset:33680
	ds_read_u16 v232, v194 offset:34080
	ds_read_u16 v233, v194 offset:34480
	ds_read_u16 v234, v194 offset:39680
	ds_read_u16 v235, v194 offset:40080
	ds_read_u16 v236, v194 offset:40480
	ds_read_u16 v237, v194 offset:40880
	ds_read_u16 v238, v194 offset:46080
	ds_read_u16 v239, v194 offset:46480
	ds_read_u16 v240, v194 offset:46880
	ds_read_u16 v241, v194 offset:47280
	s_waitcnt lgkmcnt(15)
	v_mfma_f32_16x16x32_bf16 v[124:127], v[120:123], v[20:23], v[214:217]
	v_add_f32_e32 v148, v148, v170
	v_add_f32_e32 v144, v144, v171
	v_min_f32_e64 v148, -v148, s93
	v_min_f32_e64 v144, -v144, s93
	v_mul_f32_e32 v148, 0x3fb8aa3b, v148
	v_mul_f32_e32 v144, 0x3fb8aa3b, v144
	v_exp_f32_e32 v148, v148
	v_exp_f32_e32 v144, v144
	v_mfma_f32_16x16x32_bf16 v[120:123], v[120:123], v[68:71], v[210:213]
	v_add_f32_e32 v145, v145, v171
	v_add_f32_e32 v148, 1.0, v148
	v_add_f32_e32 v144, 1.0, v144
	v_mul_f32_e32 v210, v148, v144
	v_rcp_f32_e32 v210, v210
	v_min_f32_e64 v145, -v145, s93
	v_mul_f32_e32 v145, 0x3fb8aa3b, v145
	v_mul_f32_e32 v144, v144, v210
	v_mul_f32_e32 v144, v205, v144
	v_mul_f32_e32 v144, 0x3fb8aa3b, v144
	v_exp_f32_e32 v144, v144
	v_mul_f32_e32 v148, v148, v210
	s_waitcnt lgkmcnt(0)
	v_lshlrev_b32_e32 v211, 16, v226
	v_mul_f32_e32 v148, v148, v211
	v_sub_f32_e32 v210, 1.0, v144
	v_add_f32_e32 v144, 1.0, v144
	v_mul_f32_e32 v144, v210, v144
	v_max_f32_e32 v144, 0, v144
	v_sqrt_f32_e32 v144, v144
	v_exp_f32_e32 v145, v145
	v_add_f32_e32 v140, v140, v170
	v_add_f32_e32 v136, v136, v171
	v_mul_f32_e32 v144, v148, v144
	v_cvt_pk_bf16_f32 v144, v144, s0
	ds_write_b16 v196, v144
	v_add_f32_e32 v144, v149, v170
	v_min_f32_e64 v144, -v144, s93
	v_mul_f32_e32 v144, 0x3fb8aa3b, v144
	v_exp_f32_e32 v144, v144
	v_cvt_pk_bf16_f32 v148, v210, s0
	v_add_f32_e32 v145, 1.0, v145
	ds_write_b16 v195, v148
	v_add_f32_e32 v144, 1.0, v144
	v_mul_f32_e32 v148, v144, v145
	v_rcp_f32_e32 v148, v148
	v_min_f32_e64 v140, -v140, s93
	v_min_f32_e64 v136, -v136, s93
	v_mul_f32_e32 v145, v145, v148
	v_mul_f32_e32 v145, v205, v145
	v_mul_f32_e32 v145, 0x3fb8aa3b, v145
	v_exp_f32_e32 v145, v145
	v_mul_f32_e32 v144, v144, v148
	v_lshlrev_b32_e32 v149, 16, v227
	v_mul_f32_e32 v144, v144, v149
	v_sub_f32_e32 v148, 1.0, v145
	v_add_f32_e32 v145, 1.0, v145
	v_mul_f32_e32 v145, v148, v145
	v_max_f32_e32 v145, 0, v145
	v_sqrt_f32_e32 v145, v145
	v_mul_f32_e32 v140, 0x3fb8aa3b, v140
	v_mul_f32_e32 v136, 0x3fb8aa3b, v136
	v_exp_f32_e32 v140, v140
	v_mul_f32_e32 v144, v144, v145
	v_cvt_pk_bf16_f32 v145, v148, s0
	v_cvt_pk_bf16_f32 v144, v144, s0
	ds_write_b16 v195, v145 offset:400
	ds_write_b16 v196, v144 offset:400
	v_add_f32_e32 v144, v150, v170
	v_add_f32_e32 v145, v146, v171
	v_min_f32_e64 v144, -v144, s93
	v_min_f32_e64 v145, -v145, s93
	v_mul_f32_e32 v144, 0x3fb8aa3b, v144
	v_mul_f32_e32 v145, 0x3fb8aa3b, v145
	v_exp_f32_e32 v144, v144
	v_exp_f32_e32 v145, v145
	v_exp_f32_e32 v136, v136
	v_add_f32_e32 v144, 1.0, v144
	v_add_f32_e32 v145, 1.0, v145
	v_mul_f32_e32 v146, v144, v145
; #define LAS __attribute__((address_space(3)))
; DI unsigned pk2(float a, float b) { f32x2 v = {a, b}; bf2_t r = __builtin_convertvector(v, bf2_t); return __builtin_bit_cast(unsigned, r); }
; DI void phase_rglru(const Params& p, unsigned char* shm) {
;     ...
;                     const int ch = chb + 16 * u + fr;
;                     const float ba = gb[ch], bx = gb[192 + ch], sp = gb[384 + ch];
; #pragma unroll
;                     for (int mt = 0; mt < 4; ++mt)
; #pragma unroll
;                         for (int j = 0; j < 4; ++j) {
;                             const int t = 16 * mt + 4 * fq + j;
;                             const float ea = 1.f + __expf(fminf(-(acc[mt][0][j] + ba), 40.f)), ex = 1.f + __expf(fminf(-(acc[mt][1][j] + bx), 40.f));
;                             const float inv = __builtin_amdgcn_rcpf(ea * ex);
;                             const float r = inv * ex, ig = inv * ea;
;                             const float av = __expf(r * sp), om = 1.f - av;
;                             const float xcv = __uint_as_float((unsigned)*(const LAS bf16_t*)(lds + XC + t * TR + ch * 2) << 16);
;                             const float bt = __builtin_amdgcn_sqrtf(fmaxf(om * (1.f + av), 0.f)) * (ig * xcv);
;                             *(LAS bf16_t*)(lds + LAo + t * TR + ch * 2) = (bf16_t)(pk2(om, 0.f) & 0xffffu);
;                             *(LAS bf16_t*)(lds + BTo + t * TR + ch * 2) = (bf16_t)(pk2(bt, 0.f) & 0xffffu);
;                         }
	v_rcp_f32_e32 v146, v146
	v_lshlrev_b32_e32 v148, 16, v228
	v_add_f32_e32 v140, 1.0, v140
	v_add_f32_e32 v136, 1.0, v136
	v_mul_f32_e32 v145, v145, v146
	v_mul_f32_e32 v145, v205, v145
	v_mul_f32_e32 v145, 0x3fb8aa3b, v145
	v_exp_f32_e32 v145, v145
	v_mul_f32_e32 v144, v144, v146
	v_mul_f32_e32 v144, v144, v148
	v_add_f32_e32 v137, v137, v171
	v_sub_f32_e32 v146, 1.0, v145
	v_add_f32_e32 v145, 1.0, v145
	v_mul_f32_e32 v145, v146, v145
	v_max_f32_e32 v145, 0, v145
	v_sqrt_f32_e32 v145, v145
	v_min_f32_e64 v137, -v137, s93
	v_mul_f32_e32 v137, 0x3fb8aa3b, v137
	v_exp_f32_e32 v137, v137
	v_mul_f32_e32 v144, v144, v145
	v_cvt_pk_bf16_f32 v145, v146, s0
	v_cvt_pk_bf16_f32 v144, v144, s0
	ds_write_b16 v195, v145 offset:800
	ds_write_b16 v196, v144 offset:800
	v_add_f32_e32 v144, v151, v170
	v_add_f32_e32 v145, v147, v171
	v_min_f32_e64 v144, -v144, s93
	v_min_f32_e64 v145, -v145, s93
	v_mul_f32_e32 v144, 0x3fb8aa3b, v144
	v_mul_f32_e32 v145, 0x3fb8aa3b, v145
	v_exp_f32_e32 v144, v144
	v_exp_f32_e32 v145, v145
	v_add_f32_e32 v137, 1.0, v137
	v_add_f32_e32 v144, 1.0, v144
	v_add_f32_e32 v145, 1.0, v145
	v_mul_f32_e32 v146, v144, v145
	v_rcp_f32_e32 v146, v146
	v_lshlrev_b32_e32 v147, 16, v229
	v_add_f32_e32 v124, v124, v170
	v_add_f32_e32 v120, v120, v171
	v_mul_f32_e32 v145, v145, v146
	v_mul_f32_e32 v145, v205, v145
	v_mul_f32_e32 v145, 0x3fb8aa3b, v145
	v_exp_f32_e32 v145, v145
	v_mul_f32_e32 v144, v144, v146
	v_mul_f32_e32 v144, v144, v147
	v_min_f32_e64 v124, -v124, s93
	v_sub_f32_e32 v146, 1.0, v145
	v_add_f32_e32 v145, 1.0, v145
	v_mul_f32_e32 v145, v146, v145
	v_max_f32_e32 v145, 0, v145
	v_sqrt_f32_e32 v145, v145
	v_min_f32_e64 v120, -v120, s93
	v_mul_f32_e32 v124, 0x3fb8aa3b, v124
	v_mul_f32_e32 v120, 0x3fb8aa3b, v120
	v_mul_f32_e32 v144, v144, v145
	v_cvt_pk_bf16_f32 v144, v144, s0
	ds_write_b16 v196, v144 offset:1200
	v_mul_f32_e32 v144, v140, v136
	v_rcp_f32_e32 v144, v144
	v_cvt_pk_bf16_f32 v145, v146, s0
	ds_write_b16 v195, v145 offset:1200
	v_exp_f32_e32 v124, v124
	v_mul_f32_e32 v145, v136, v144
	v_mul_f32_e32 v136, v140, v144
	v_mul_f32_e32 v140, v205, v145
	v_mul_f32_e32 v140, 0x3fb8aa3b, v140
	v_exp_f32_e32 v144, v140
	v_exp_f32_e32 v120, v120
	v_add_f32_e32 v124, 1.0, v124
	v_sub_f32_e32 v140, 1.0, v144
	v_add_f32_e32 v144, 1.0, v144
	v_mul_f32_e32 v144, v140, v144
	v_max_f32_e32 v144, 0, v144
	v_sqrt_f32_e32 v144, v144
	v_lshlrev_b32_e32 v145, 16, v230
	v_mul_f32_e32 v136, v136, v145
	v_cvt_pk_bf16_f32 v140, v140, s0
	v_mul_f32_e32 v136, v144, v136
	v_cvt_pk_bf16_f32 v136, v136, s0
	ds_write_b16 v196, v136 offset:6400
	v_add_f32_e32 v136, v141, v170
	v_min_f32_e64 v136, -v136, s93
	v_mul_f32_e32 v136, 0x3fb8aa3b, v136
	v_exp_f32_e32 v136, v136
	ds_write_b16 v195, v140 offset:6400
	v_add_f32_e32 v120, 1.0, v120
	v_add_f32_e32 v136, 1.0, v136
	v_mul_f32_e32 v140, v136, v137
	v_rcp_f32_e32 v140, v140
	v_lshlrev_b32_e32 v141, 16, v231
	v_add_f32_e32 v121, v121, v171
	v_min_f32_e64 v121, -v121, s93
	v_mul_f32_e32 v137, v137, v140
	v_mul_f32_e32 v137, v205, v137
	v_mul_f32_e32 v137, 0x3fb8aa3b, v137
	v_exp_f32_e32 v137, v137
	v_mul_f32_e32 v136, v136, v140
	v_mul_f32_e32 v136, v136, v141
	v_mul_f32_e32 v121, 0x3fb8aa3b, v121
	v_sub_f32_e32 v140, 1.0, v137
	v_add_f32_e32 v137, 1.0, v137
	v_mul_f32_e32 v137, v140, v137
	v_max_f32_e32 v137, 0, v137
	v_sqrt_f32_e32 v137, v137
	v_exp_f32_e32 v121, v121
	v_mfma_f32_16x16x32_bf16 v[132:135], v[128:131], v[20:23], v[218:221]
	v_mul_f32_e32 v136, v137, v136
	v_cvt_pk_bf16_f32 v137, v140, s0
	v_cvt_pk_bf16_f32 v136, v136, s0
	ds_write_b16 v195, v137 offset:6800
	ds_write_b16 v196, v136 offset:6800
	v_add_f32_e32 v136, v142, v170
	v_add_f32_e32 v137, v138, v171
	v_min_f32_e64 v136, -v136, s93
	v_min_f32_e64 v137, -v137, s93
	v_mul_f32_e32 v136, 0x3fb8aa3b, v136
	v_mul_f32_e32 v137, 0x3fb8aa3b, v137
	v_exp_f32_e32 v136, v136
	v_exp_f32_e32 v137, v137
	v_add_f32_e32 v121, 1.0, v121
	v_add_f32_e32 v136, 1.0, v136
	v_add_f32_e32 v137, 1.0, v137
	v_mul_f32_e32 v138, v136, v137
	v_rcp_f32_e32 v138, v138
	v_lshlrev_b32_e32 v140, 16, v232
	v_mfma_f32_16x16x32_bf16 v[128:131], v[128:131], v[68:71], v[222:225]
	v_mul_f32_e32 v137, v137, v138
	v_mul_f32_e32 v137, v205, v137
	v_mul_f32_e32 v137, 0x3fb8aa3b, v137
	v_exp_f32_e32 v137, v137
	v_mul_f32_e32 v136, v136, v138
	v_mul_f32_e32 v136, v136, v140
	v_sub_f32_e32 v138, 1.0, v137
	v_add_f32_e32 v137, 1.0, v137
	v_mul_f32_e32 v137, v138, v137
	v_max_f32_e32 v137, 0, v137
	v_sqrt_f32_e32 v137, v137
	s_nop 0
	v_mul_f32_e32 v136, v137, v136
	v_cvt_pk_bf16_f32 v137, v138, s0
	v_cvt_pk_bf16_f32 v136, v136, s0
	ds_write_b16 v195, v137 offset:7200
	ds_write_b16 v196, v136 offset:7200
	v_add_f32_e32 v136, v143, v170
	v_add_f32_e32 v137, v139, v171
	v_min_f32_e64 v136, -v136, s93
	v_min_f32_e64 v137, -v137, s93
	v_mul_f32_e32 v136, 0x3fb8aa3b, v136
	v_mul_f32_e32 v137, 0x3fb8aa3b, v137
	v_exp_f32_e32 v136, v136
	v_exp_f32_e32 v137, v137
	v_add_f32_e32 v136, 1.0, v136
	v_add_f32_e32 v137, 1.0, v137
	v_mul_f32_e32 v138, v136, v137
	v_rcp_f32_e32 v138, v138
	v_lshlrev_b32_e32 v139, 16, v233
	v_mul_f32_e32 v137, v137, v138
	v_mul_f32_e32 v137, v205, v137
	v_mul_f32_e32 v137, 0x3fb8aa3b, v137
	v_exp_f32_e32 v137, v137
	v_mul_f32_e32 v136, v136, v138
	v_mul_f32_e32 v136, v136, v139
	v_sub_f32_e32 v138, 1.0, v137
	v_add_f32_e32 v137, 1.0, v137
	v_mul_f32_e32 v137, v138, v137
	v_max_f32_e32 v137, 0, v137
	v_sqrt_f32_e32 v137, v137
	s_nop 0
	v_mul_f32_e32 v136, v137, v136
	v_cvt_pk_bf16_f32 v136, v136, s0
	ds_write_b16 v196, v136 offset:7600
	v_mul_f32_e32 v136, v124, v120
	v_rcp_f32_e32 v136, v136
	v_cvt_pk_bf16_f32 v137, v138, s0
	ds_write_b16 v195, v137 offset:7600
; #define LAS __attribute__((address_space(3)))
; DI unsigned pk2(float a, float b) { f32x2 v = {a, b}; bf2_t r = __builtin_convertvector(v, bf2_t); return __builtin_bit_cast(unsigned, r); }
; DI void phase_rglru(const Params& p, unsigned char* shm) {
;     ...
;                     if (u == 1 && w >= 4) break;
;                     f32x4 acc[4][2];
; #pragma unroll
;                     for (int mt = 0; mt < 4; ++mt) { acc[mt][0] = (f32x4){0.f, 0.f, 0.f, 0.f}; acc[mt][1] = (f32x4){0.f, 0.f, 0.f, 0.f}; }
; #pragma unroll
;                     for (int kk = 0; kk < 6; ++kk)
; #pragma unroll
;                         for (int mt = 0; mt < 4; ++mt) {
;                             const bf16x8 af = *(const LAS bf16x8*)(lds + XC + (16 * mt + fr) * TR + (32 * kk + 8 * fq) * 2);
;                             acc[mt][0] = __builtin_amdgcn_mfma_f32_16x16x32_bf16(af, Bf[u][kk], acc[mt][0], 0, 0, 0);
;                             acc[mt][1] = __builtin_amdgcn_mfma_f32_16x16x32_bf16(af, Bf[2 + u][kk], acc[mt][1], 0, 0, 0);
;                         }
;                     const int ch = chb + 16 * u + fr;
;                     const float ba = gb[ch], bx = gb[192 + ch], sp = gb[384 + ch];
; #pragma unroll
;                     for (int mt = 0; mt < 4; ++mt)
; #pragma unroll
;                         for (int j = 0; j < 4; ++j) {
;                             const int t = 16 * mt + 4 * fq + j;
;                             const float ea = 1.f + __expf(fminf(-(acc[mt][0][j] + ba), 40.f)), ex = 1.f + __expf(fminf(-(acc[mt][1][j] + bx), 40.f));
;                             const float inv = __builtin_amdgcn_rcpf(ea * ex);
;                             const float r = inv * ex, ig = inv * ea;
;                             const float av = __expf(r * sp), om = 1.f - av;
;                             const float xcv = __uint_as_float((unsigned)*(const LAS bf16_t*)(lds + XC + t * TR + ch * 2) << 16);
;                             const float bt = __builtin_amdgcn_sqrtf(fmaxf(om * (1.f + av), 0.f)) * (ig * xcv);
;                             *(LAS bf16_t*)(lds + LAo + t * TR + ch * 2) = (bf16_t)(pk2(om, 0.f) & 0xffffu);
;                             *(LAS bf16_t*)(lds + BTo + t * TR + ch * 2) = (bf16_t)(pk2(bt, 0.f) & 0xffffu);
;                         }
	v_mul_f32_e32 v120, v120, v136
	v_mul_f32_e32 v120, v205, v120
	v_mul_f32_e32 v120, 0x3fb8aa3b, v120
	v_exp_f32_e32 v120, v120
	v_mul_f32_e32 v124, v124, v136
	v_lshlrev_b32_e32 v137, 16, v234
	v_mul_f32_e32 v124, v124, v137
	v_sub_f32_e32 v136, 1.0, v120
	v_add_f32_e32 v120, 1.0, v120
	v_mul_f32_e32 v120, v136, v120
	v_max_f32_e32 v120, 0, v120
	v_sqrt_f32_e32 v120, v120
	s_nop 0
	v_mul_f32_e32 v120, v120, v124
	v_cvt_pk_bf16_f32 v120, v120, s0
	ds_write_b16 v196, v120 offset:12800
	v_add_f32_e32 v120, v125, v170
	v_min_f32_e64 v120, -v120, s93
	v_mul_f32_e32 v120, 0x3fb8aa3b, v120
	v_exp_f32_e32 v120, v120
	v_cvt_pk_bf16_f32 v124, v136, s0
	ds_write_b16 v195, v124 offset:12800
	v_add_f32_e32 v120, 1.0, v120
	v_mul_f32_e32 v124, v120, v121
	v_rcp_f32_e32 v124, v124
	v_lshlrev_b32_e32 v125, 16, v235
	v_mul_f32_e32 v121, v121, v124
	v_mul_f32_e32 v121, v205, v121
	v_mul_f32_e32 v121, 0x3fb8aa3b, v121
	v_exp_f32_e32 v121, v121
	v_mul_f32_e32 v120, v120, v124
	v_mul_f32_e32 v120, v120, v125
	v_sub_f32_e32 v124, 1.0, v121
	v_add_f32_e32 v121, 1.0, v121
	v_mul_f32_e32 v121, v124, v121
	v_max_f32_e32 v121, 0, v121
	v_sqrt_f32_e32 v121, v121
	s_nop 0
	v_mul_f32_e32 v120, v121, v120
	v_cvt_pk_bf16_f32 v121, v124, s0
	v_cvt_pk_bf16_f32 v120, v120, s0
	ds_write_b16 v195, v121 offset:13200
	ds_write_b16 v196, v120 offset:13200
	v_add_f32_e32 v120, v126, v170
	v_add_f32_e32 v121, v122, v171
	v_min_f32_e64 v120, -v120, s93
	v_min_f32_e64 v121, -v121, s93
	v_mul_f32_e32 v120, 0x3fb8aa3b, v120
	v_mul_f32_e32 v121, 0x3fb8aa3b, v121
	v_exp_f32_e32 v120, v120
	v_exp_f32_e32 v121, v121
	v_add_f32_e32 v120, 1.0, v120
	v_add_f32_e32 v121, 1.0, v121
	v_mul_f32_e32 v122, v120, v121
	v_rcp_f32_e32 v122, v122
	v_lshlrev_b32_e32 v124, 16, v236
	v_mul_f32_e32 v121, v121, v122
	v_mul_f32_e32 v121, v205, v121
	v_mul_f32_e32 v121, 0x3fb8aa3b, v121
	v_exp_f32_e32 v121, v121
	v_mul_f32_e32 v120, v120, v122
	v_mul_f32_e32 v120, v120, v124
	v_sub_f32_e32 v122, 1.0, v121
	v_add_f32_e32 v121, 1.0, v121
	v_mul_f32_e32 v121, v122, v121
	v_max_f32_e32 v121, 0, v121
	v_sqrt_f32_e32 v121, v121
	s_nop 0
	v_mul_f32_e32 v120, v121, v120
	v_cvt_pk_bf16_f32 v121, v122, s0
	v_cvt_pk_bf16_f32 v120, v120, s0
	ds_write_b16 v195, v121 offset:13600
	ds_write_b16 v196, v120 offset:13600
	v_add_f32_e32 v120, v127, v170
	v_add_f32_e32 v121, v123, v171
	v_min_f32_e64 v120, -v120, s93
	v_min_f32_e64 v121, -v121, s93
	v_mul_f32_e32 v120, 0x3fb8aa3b, v120
	v_mul_f32_e32 v121, 0x3fb8aa3b, v121
	v_exp_f32_e32 v120, v120
	v_exp_f32_e32 v121, v121
	v_add_f32_e32 v120, 1.0, v120
	v_add_f32_e32 v121, 1.0, v121
	v_mul_f32_e32 v122, v120, v121
	v_rcp_f32_e32 v122, v122
	v_lshlrev_b32_e32 v123, 16, v237
	v_mul_f32_e32 v121, v121, v122
	v_mul_f32_e32 v121, v205, v121
	v_mul_f32_e32 v121, 0x3fb8aa3b, v121
	v_exp_f32_e32 v121, v121
	v_mul_f32_e32 v120, v120, v122
	v_mul_f32_e32 v120, v120, v123
	v_sub_f32_e32 v122, 1.0, v121
	v_add_f32_e32 v121, 1.0, v121
	v_mul_f32_e32 v121, v122, v121
	v_max_f32_e32 v121, 0, v121
	v_sqrt_f32_e32 v121, v121
	v_lshlrev_b32_e32 v123, 16, v238
	v_mul_f32_e32 v120, v121, v120
	v_cvt_pk_bf16_f32 v121, v122, s0
	v_cvt_pk_bf16_f32 v120, v120, s0
	ds_write_b16 v195, v121 offset:14000
	ds_write_b16 v196, v120 offset:14000
	v_add_f32_e32 v120, v132, v170
	v_add_f32_e32 v121, v128, v171
	v_min_f32_e64 v120, -v120, s93
	v_min_f32_e64 v121, -v121, s93
	v_mul_f32_e32 v120, 0x3fb8aa3b, v120
	v_mul_f32_e32 v121, 0x3fb8aa3b, v121
	v_exp_f32_e32 v120, v120
	v_exp_f32_e32 v121, v121
	v_add_f32_e32 v120, 1.0, v120
	v_add_f32_e32 v121, 1.0, v121
	v_mul_f32_e32 v122, v120, v121
	v_rcp_f32_e32 v122, v122
	s_nop 0
	v_mul_f32_e32 v121, v121, v122
	v_mul_f32_e32 v121, v205, v121
	v_mul_f32_e32 v121, 0x3fb8aa3b, v121
	v_exp_f32_e32 v121, v121
	v_mul_f32_e32 v120, v120, v122
	v_mul_f32_e32 v120, v120, v123
	v_sub_f32_e32 v122, 1.0, v121
	v_add_f32_e32 v121, 1.0, v121
	v_mul_f32_e32 v121, v122, v121
	v_max_f32_e32 v121, 0, v121
	v_sqrt_f32_e32 v121, v121
	v_lshlrev_b32_e32 v123, 16, v239
	v_mul_f32_e32 v120, v121, v120
	v_cvt_pk_bf16_f32 v121, v122, s0
	v_cvt_pk_bf16_f32 v120, v120, s0
	ds_write_b16 v195, v121 offset:19200
	ds_write_b16 v196, v120 offset:19200
	v_add_f32_e32 v120, v133, v170
	v_add_f32_e32 v121, v129, v171
	v_min_f32_e64 v120, -v120, s93
	v_min_f32_e64 v121, -v121, s93
	v_mul_f32_e32 v120, 0x3fb8aa3b, v120
	v_mul_f32_e32 v121, 0x3fb8aa3b, v121
	v_exp_f32_e32 v120, v120
	v_exp_f32_e32 v121, v121
	v_add_f32_e32 v120, 1.0, v120
	v_add_f32_e32 v121, 1.0, v121
	v_mul_f32_e32 v122, v120, v121
	v_rcp_f32_e32 v122, v122
	s_nop 0
	v_mul_f32_e32 v121, v121, v122
	v_mul_f32_e32 v121, v205, v121
	v_mul_f32_e32 v121, 0x3fb8aa3b, v121
	v_exp_f32_e32 v121, v121
	v_mul_f32_e32 v120, v120, v122
	v_mul_f32_e32 v120, v120, v123
	v_sub_f32_e32 v122, 1.0, v121
	v_add_f32_e32 v121, 1.0, v121
	v_mul_f32_e32 v121, v122, v121
	v_max_f32_e32 v121, 0, v121
	v_sqrt_f32_e32 v121, v121
	v_lshlrev_b32_e32 v123, 16, v240
	v_mul_f32_e32 v120, v121, v120
	v_cvt_pk_bf16_f32 v121, v122, s0
	v_cvt_pk_bf16_f32 v120, v120, s0
	ds_write_b16 v195, v121 offset:19600
	ds_write_b16 v196, v120 offset:19600
	v_add_f32_e32 v120, v134, v170
	v_add_f32_e32 v121, v130, v171
	v_min_f32_e64 v120, -v120, s93
	v_min_f32_e64 v121, -v121, s93
	v_mul_f32_e32 v120, 0x3fb8aa3b, v120
	v_mul_f32_e32 v121, 0x3fb8aa3b, v121
	v_exp_f32_e32 v120, v120
	v_exp_f32_e32 v121, v121
	v_add_f32_e32 v120, 1.0, v120
	v_add_f32_e32 v121, 1.0, v121
	v_mul_f32_e32 v122, v120, v121
	v_rcp_f32_e32 v122, v122
	s_nop 0
	v_mul_f32_e32 v121, v121, v122
	v_mul_f32_e32 v121, v205, v121
	v_mul_f32_e32 v121, 0x3fb8aa3b, v121
	v_exp_f32_e32 v121, v121
	v_mul_f32_e32 v120, v120, v122
	v_mul_f32_e32 v120, v120, v123
	v_sub_f32_e32 v122, 1.0, v121
	v_add_f32_e32 v121, 1.0, v121
	v_mul_f32_e32 v121, v122, v121
	v_max_f32_e32 v121, 0, v121
	v_sqrt_f32_e32 v121, v121
	v_lshlrev_b32_e32 v123, 16, v241
	v_mul_f32_e32 v120, v121, v120
	v_cvt_pk_bf16_f32 v121, v122, s0
	v_cvt_pk_bf16_f32 v120, v120, s0
	ds_write_b16 v195, v121 offset:20000
	ds_write_b16 v196, v120 offset:20000
	v_add_f32_e32 v120, v135, v170
	v_add_f32_e32 v121, v131, v171
	v_min_f32_e64 v120, -v120, s93
	v_min_f32_e64 v121, -v121, s93
	v_mul_f32_e32 v120, 0x3fb8aa3b, v120
	v_mul_f32_e32 v121, 0x3fb8aa3b, v121
	v_exp_f32_e32 v120, v120
	v_exp_f32_e32 v121, v121
	v_add_f32_e32 v120, 1.0, v120
	v_add_f32_e32 v121, 1.0, v121
	v_mul_f32_e32 v122, v120, v121
	v_rcp_f32_e32 v122, v122
	s_nop 0
	v_mul_f32_e32 v121, v121, v122
	v_mul_f32_e32 v121, v205, v121
	v_mul_f32_e32 v121, 0x3fb8aa3b, v121
	v_mul_f32_e32 v120, v120, v122
	v_exp_f32_e32 v122, v121
	v_mul_f32_e32 v120, v120, v123
	v_sub_f32_e32 v121, 1.0, v122
	v_add_f32_e32 v122, 1.0, v122
	v_mul_f32_e32 v122, v121, v122
	v_max_f32_e32 v122, 0, v122
	v_sqrt_f32_e32 v122, v122
	v_cvt_pk_bf16_f32 v121, v121, s0
	ds_write_b16 v195, v121 offset:20400
	v_mul_f32_e32 v120, v122, v120
	v_cvt_pk_bf16_f32 v120, v120, s0
	ds_write_b16 v196, v120 offset:20400
	s_andn2_b64 vcc, exec, s[12:13]
	s_cbranch_vccnz .Lgates_b
; #define LAS __attribute__((address_space(3)))
; DI unsigned pk2(float a, float b) { f32x2 v = {a, b}; bf2_t r = __builtin_convertvector(v, bf2_t); return __builtin_bit_cast(unsigned, r); }
; DI void phase_rglru(const Params& p, unsigned char* shm) {
;     ...
;                 for (int u = 0; u < 2; ++u) {
;                     if (u == 1 && w >= 4) break;
;                     f32x4 acc[4][2];
; #pragma unroll
;                     for (int mt = 0; mt < 4; ++mt) { acc[mt][0] = (f32x4){0.f, 0.f, 0.f, 0.f}; acc[mt][1] = (f32x4){0.f, 0.f, 0.f, 0.f}; }
; #pragma unroll
;                     for (int kk = 0; kk < 6; ++kk)
; #pragma unroll
;                         for (int mt = 0; mt < 4; ++mt) {
;                             const bf16x8 af = *(const LAS bf16x8*)(lds + XC + (16 * mt + fr) * TR + (32 * kk + 8 * fq) * 2);
;                             acc[mt][0] = __builtin_amdgcn_mfma_f32_16x16x32_bf16(af, Bf[u][kk], acc[mt][0], 0, 0, 0);
;                             acc[mt][1] = __builtin_amdgcn_mfma_f32_16x16x32_bf16(af, Bf[2 + u][kk], acc[mt][1], 0, 0, 0);
;                         }
;                     const int ch = chb + 16 * u + fr;
;                     const float ba = gb[ch], bx = gb[192 + ch], sp = gb[384 + ch];
; #pragma unroll
;                     for (int mt = 0; mt < 4; ++mt)
; #pragma unroll
;                         for (int j = 0; j < 4; ++j) {
;                             const int t = 16 * mt + 4 * fq + j;
;                             const float ea = 1.f + __expf(fminf(-(acc[mt][0][j] + ba), 40.f)), ex = 1.f + __expf(fminf(-(acc[mt][1][j] + bx), 40.f));
;                             const float inv = __builtin_amdgcn_rcpf(ea * ex);
;                             const float r = inv * ex, ig = inv * ea;
;                             const float av = __expf(r * sp), om = 1.f - av;
;                             const float xcv = __uint_as_float((unsigned)*(const LAS bf16_t*)(lds + XC + t * TR + ch * 2) << 16);
;                             const float bt = __builtin_amdgcn_sqrtf(fmaxf(om * (1.f + av), 0.f)) * (ig * xcv);
;                             *(LAS bf16_t*)(lds + LAo + t * TR + ch * 2) = (bf16_t)(pk2(om, 0.f) & 0xffffu);
;                             *(LAS bf16_t*)(lds + BTo + t * TR + ch * 2) = (bf16_t)(pk2(bt, 0.f) & 0xffffu);
;                         }
	ds_read_b128 v[120:123], v204 offset:26880
	ds_read_b128 v[124:127], v204 offset:33280
	ds_read_b128 v[128:131], v204 offset:26944
	ds_read_b128 v[132:135], v204 offset:33344
	ds_read_b128 v[226:229], v204 offset:27008
	s_waitcnt lgkmcnt(4)
	v_mfma_f32_16x16x32_bf16 v[148:151], v[120:123], v[24:27], 0
	v_mfma_f32_16x16x32_bf16 v[144:147], v[120:123], v[72:75], 0
	ds_read_b128 v[230:233], v204 offset:33408
	s_waitcnt lgkmcnt(4)
	v_mfma_f32_16x16x32_bf16 v[140:143], v[124:127], v[24:27], 0
	v_mfma_f32_16x16x32_bf16 v[136:139], v[124:127], v[72:75], 0
	ds_read_b128 v[120:123], v204 offset:27072
	s_waitcnt lgkmcnt(4)
	v_mfma_f32_16x16x32_bf16 v[148:151], v[128:131], v[28:31], v[148:151]
	v_mfma_f32_16x16x32_bf16 v[144:147], v[128:131], v[76:79], v[144:147]
	ds_read_b128 v[124:127], v204 offset:33472
	s_waitcnt lgkmcnt(4)
	v_mfma_f32_16x16x32_bf16 v[140:143], v[132:135], v[28:31], v[140:143]
	v_mfma_f32_16x16x32_bf16 v[136:139], v[132:135], v[76:79], v[136:139]
	ds_read_b128 v[128:131], v204 offset:27136
	s_waitcnt lgkmcnt(4)
	v_mfma_f32_16x16x32_bf16 v[148:151], v[226:229], v[32:35], v[148:151]
	v_mfma_f32_16x16x32_bf16 v[144:147], v[226:229], v[80:83], v[144:147]
	ds_read_b128 v[132:135], v204 offset:33536
	s_waitcnt lgkmcnt(4)
	v_mfma_f32_16x16x32_bf16 v[140:143], v[230:233], v[32:35], v[140:143]
	v_mfma_f32_16x16x32_bf16 v[136:139], v[230:233], v[80:83], v[136:139]
	ds_read_b128 v[226:229], v204 offset:27200
	s_waitcnt lgkmcnt(4)
	v_mfma_f32_16x16x32_bf16 v[148:151], v[120:123], v[36:39], v[148:151]
	v_mfma_f32_16x16x32_bf16 v[144:147], v[120:123], v[84:87], v[144:147]
	ds_read_b128 v[230:233], v204 offset:33600
	s_waitcnt lgkmcnt(4)
	v_mfma_f32_16x16x32_bf16 v[140:143], v[124:127], v[36:39], v[140:143]
	v_mfma_f32_16x16x32_bf16 v[136:139], v[124:127], v[84:87], v[136:139]
	s_waitcnt lgkmcnt(3)
	v_mfma_f32_16x16x32_bf16 v[148:151], v[128:131], v[40:43], v[148:151]
	v_mfma_f32_16x16x32_bf16 v[144:147], v[128:131], v[88:91], v[144:147]
	s_waitcnt lgkmcnt(2)
	v_mfma_f32_16x16x32_bf16 v[140:143], v[132:135], v[40:43], v[140:143]
	v_mfma_f32_16x16x32_bf16 v[136:139], v[132:135], v[88:91], v[136:139]
	s_waitcnt lgkmcnt(1)
	v_mfma_f32_16x16x32_bf16 v[148:151], v[226:229], v[44:47], v[148:151]
	v_mfma_f32_16x16x32_bf16 v[144:147], v[226:229], v[92:95], v[144:147]
	s_waitcnt lgkmcnt(0)
	v_mfma_f32_16x16x32_bf16 v[140:143], v[230:233], v[44:47], v[140:143]
	v_mfma_f32_16x16x32_bf16 v[136:139], v[230:233], v[92:95], v[136:139]
	s_nop 1
	ds_read2st64_b32 v[170:171], v185 offset1:3
	ds_read_b32 v205, v185 offset:1536
	ds_read_u16 v226, v197 offset:26880
	ds_read_u16 v227, v197 offset:27280
	ds_read_u16 v228, v197 offset:27680
	ds_read_u16 v229, v197 offset:28080
	ds_read_u16 v230, v197 offset:33280
	ds_read_u16 v231, v197 offset:33680
	ds_read_u16 v232, v197 offset:34080
	ds_read_u16 v233, v197 offset:34480
	ds_read_u16 v234, v197 offset:39680
	ds_read_u16 v235, v197 offset:40080
	ds_read_u16 v236, v197 offset:40480
	ds_read_u16 v237, v197 offset:40880
	ds_read_u16 v238, v197 offset:46080
	ds_read_u16 v239, v197 offset:46480
	ds_read_u16 v240, v197 offset:46880
	ds_read_u16 v241, v197 offset:47280
	s_waitcnt lgkmcnt(15)
	v_add_f32_e32 v148, v148, v170
	v_add_f32_e32 v144, v144, v171
	v_min_f32_e64 v148, -v148, s93
	v_min_f32_e64 v144, -v144, s93
	v_mul_f32_e32 v148, 0x3fb8aa3b, v148
	v_mul_f32_e32 v144, 0x3fb8aa3b, v144
	v_exp_f32_e32 v148, v148
	v_exp_f32_e32 v144, v144
	v_add_f32_e32 v145, v145, v171
	v_add_f32_e32 v148, 1.0, v148
	v_add_f32_e32 v144, 1.0, v144
	v_mul_f32_e32 v210, v148, v144
	v_rcp_f32_e32 v210, v210
	v_min_f32_e64 v145, -v145, s93
	v_mul_f32_e32 v145, 0x3fb8aa3b, v145
	v_mul_f32_e32 v144, v144, v210
	v_mul_f32_e32 v144, v205, v144
	v_mul_f32_e32 v144, 0x3fb8aa3b, v144
	v_exp_f32_e32 v144, v144
	v_mul_f32_e32 v148, v148, v210
	s_waitcnt lgkmcnt(0)
	v_lshlrev_b32_e32 v211, 16, v226
	v_mul_f32_e32 v148, v148, v211
	v_sub_f32_e32 v210, 1.0, v144
	v_add_f32_e32 v144, 1.0, v144
	v_mul_f32_e32 v144, v210, v144
	v_max_f32_e32 v144, 0, v144
	v_sqrt_f32_e32 v144, v144
	v_exp_f32_e32 v145, v145
	v_add_f32_e32 v140, v140, v170
	v_add_f32_e32 v136, v136, v171
	v_mul_f32_e32 v144, v148, v144
	v_cvt_pk_bf16_f32 v144, v144, s0
	ds_write_b16 v199, v144
	v_add_f32_e32 v144, v149, v170
	v_min_f32_e64 v144, -v144, s93
	v_mul_f32_e32 v144, 0x3fb8aa3b, v144
	v_exp_f32_e32 v144, v144
	v_cvt_pk_bf16_f32 v148, v210, s0
	v_add_f32_e32 v145, 1.0, v145
	ds_write_b16 v198, v148
	v_add_f32_e32 v144, 1.0, v144
	v_mul_f32_e32 v148, v144, v145
	v_rcp_f32_e32 v148, v148
	v_min_f32_e64 v140, -v140, s93
	v_min_f32_e64 v136, -v136, s93
	v_mul_f32_e32 v145, v145, v148
	v_mul_f32_e32 v145, v205, v145
	v_mul_f32_e32 v145, 0x3fb8aa3b, v145
	v_exp_f32_e32 v145, v145
	v_mul_f32_e32 v144, v144, v148
	v_lshlrev_b32_e32 v149, 16, v227
	v_mul_f32_e32 v144, v144, v149
	v_sub_f32_e32 v148, 1.0, v145
	v_add_f32_e32 v145, 1.0, v145
	v_mul_f32_e32 v145, v148, v145
	v_max_f32_e32 v145, 0, v145
	v_sqrt_f32_e32 v145, v145
	v_mul_f32_e32 v140, 0x3fb8aa3b, v140
	v_mul_f32_e32 v136, 0x3fb8aa3b, v136
	v_exp_f32_e32 v140, v140
	v_mul_f32_e32 v144, v144, v145
	v_cvt_pk_bf16_f32 v145, v148, s0
	v_cvt_pk_bf16_f32 v144, v144, s0
	ds_write_b16 v198, v145 offset:400
	ds_write_b16 v199, v144 offset:400
	v_add_f32_e32 v144, v150, v170
	v_add_f32_e32 v145, v146, v171
	v_min_f32_e64 v144, -v144, s93
	v_min_f32_e64 v145, -v145, s93
	v_mul_f32_e32 v144, 0x3fb8aa3b, v144
	v_mul_f32_e32 v145, 0x3fb8aa3b, v145
	v_exp_f32_e32 v144, v144
	v_exp_f32_e32 v145, v145
	v_exp_f32_e32 v136, v136
	v_add_f32_e32 v144, 1.0, v144
	v_add_f32_e32 v145, 1.0, v145
	v_mul_f32_e32 v146, v144, v145
	v_rcp_f32_e32 v146, v146
; #define LAS __attribute__((address_space(3)))
; DI unsigned pk2(float a, float b) { f32x2 v = {a, b}; bf2_t r = __builtin_convertvector(v, bf2_t); return __builtin_bit_cast(unsigned, r); }
; DI void phase_rglru(const Params& p, unsigned char* shm) {
;     ...
;                     const int ch = chb + 16 * u + fr;
;                     const float ba = gb[ch], bx = gb[192 + ch], sp = gb[384 + ch];
; #pragma unroll
;                     for (int mt = 0; mt < 4; ++mt)
; #pragma unroll
;                         for (int j = 0; j < 4; ++j) {
;                             const int t = 16 * mt + 4 * fq + j;
;                             const float ea = 1.f + __expf(fminf(-(acc[mt][0][j] + ba), 40.f)), ex = 1.f + __expf(fminf(-(acc[mt][1][j] + bx), 40.f));
;                             const float inv = __builtin_amdgcn_rcpf(ea * ex);
;                             const float r = inv * ex, ig = inv * ea;
;                             const float av = __expf(r * sp), om = 1.f - av;
;                             const float xcv = __uint_as_float((unsigned)*(const LAS bf16_t*)(lds + XC + t * TR + ch * 2) << 16);
;                             const float bt = __builtin_amdgcn_sqrtf(fmaxf(om * (1.f + av), 0.f)) * (ig * xcv);
;                             *(LAS bf16_t*)(lds + LAo + t * TR + ch * 2) = (bf16_t)(pk2(om, 0.f) & 0xffffu);
;                             *(LAS bf16_t*)(lds + BTo + t * TR + ch * 2) = (bf16_t)(pk2(bt, 0.f) & 0xffffu);
;                         }
;                     __builtin_amdgcn_sched_barrier(0);
	v_lshlrev_b32_e32 v148, 16, v228
	v_add_f32_e32 v140, 1.0, v140
	v_add_f32_e32 v136, 1.0, v136
	v_mul_f32_e32 v145, v145, v146
	v_mul_f32_e32 v145, v205, v145
	v_mul_f32_e32 v145, 0x3fb8aa3b, v145
	v_exp_f32_e32 v145, v145
	v_mul_f32_e32 v144, v144, v146
	v_mul_f32_e32 v144, v144, v148
	v_add_f32_e32 v137, v137, v171
	v_sub_f32_e32 v146, 1.0, v145
	v_add_f32_e32 v145, 1.0, v145
	v_mul_f32_e32 v145, v146, v145
	v_max_f32_e32 v145, 0, v145
	v_sqrt_f32_e32 v145, v145
	v_min_f32_e64 v137, -v137, s93
	v_mul_f32_e32 v137, 0x3fb8aa3b, v137
	v_exp_f32_e32 v137, v137
	v_mul_f32_e32 v144, v144, v145
	v_cvt_pk_bf16_f32 v145, v146, s0
	v_cvt_pk_bf16_f32 v144, v144, s0
	ds_write_b16 v198, v145 offset:800
	ds_write_b16 v199, v144 offset:800
	v_add_f32_e32 v144, v151, v170
	v_add_f32_e32 v145, v147, v171
	v_min_f32_e64 v144, -v144, s93
	v_min_f32_e64 v145, -v145, s93
	v_mul_f32_e32 v144, 0x3fb8aa3b, v144
	v_mul_f32_e32 v145, 0x3fb8aa3b, v145
	v_exp_f32_e32 v144, v144
	v_exp_f32_e32 v145, v145
	v_add_f32_e32 v137, 1.0, v137
	v_add_f32_e32 v144, 1.0, v144
	v_add_f32_e32 v145, 1.0, v145
	v_mul_f32_e32 v146, v144, v145
	v_rcp_f32_e32 v146, v146
	v_lshlrev_b32_e32 v147, 16, v229
	v_mul_f32_e32 v145, v145, v146
	v_mul_f32_e32 v145, v205, v145
	v_mul_f32_e32 v145, 0x3fb8aa3b, v145
	v_exp_f32_e32 v145, v145
	v_mul_f32_e32 v144, v144, v146
	v_mul_f32_e32 v144, v144, v147
	v_sub_f32_e32 v146, 1.0, v145
	v_add_f32_e32 v145, 1.0, v145
	v_mul_f32_e32 v145, v146, v145
	v_max_f32_e32 v145, 0, v145
	v_sqrt_f32_e32 v145, v145
	s_nop 0
	v_mul_f32_e32 v144, v144, v145
	v_cvt_pk_bf16_f32 v144, v144, s0
	ds_write_b16 v199, v144 offset:1200
	v_mul_f32_e32 v144, v140, v136
	v_rcp_f32_e32 v144, v144
	v_cvt_pk_bf16_f32 v145, v146, s0
	ds_write_b16 v198, v145 offset:1200
	v_mul_f32_e32 v145, v136, v144
	v_mul_f32_e32 v136, v140, v144
	v_mul_f32_e32 v140, v205, v145
	v_mul_f32_e32 v140, 0x3fb8aa3b, v140
	v_exp_f32_e32 v144, v140
	s_nop 0
	v_sub_f32_e32 v140, 1.0, v144
	v_add_f32_e32 v144, 1.0, v144
	v_mul_f32_e32 v144, v140, v144
	v_max_f32_e32 v144, 0, v144
	v_sqrt_f32_e32 v144, v144
	v_lshlrev_b32_e32 v145, 16, v230
	v_mul_f32_e32 v136, v136, v145
	v_cvt_pk_bf16_f32 v140, v140, s0
	v_mul_f32_e32 v136, v144, v136
	v_cvt_pk_bf16_f32 v136, v136, s0
	ds_write_b16 v199, v136 offset:6400
	v_add_f32_e32 v136, v141, v170
	v_min_f32_e64 v136, -v136, s93
	v_mul_f32_e32 v136, 0x3fb8aa3b, v136
	v_exp_f32_e32 v136, v136
	ds_write_b16 v198, v140 offset:6400
	v_add_f32_e32 v136, 1.0, v136
	v_mul_f32_e32 v140, v136, v137
	v_rcp_f32_e32 v140, v140
	v_lshlrev_b32_e32 v141, 16, v231
	v_mul_f32_e32 v137, v137, v140
	v_mul_f32_e32 v137, v205, v137
	v_mul_f32_e32 v137, 0x3fb8aa3b, v137
	v_exp_f32_e32 v137, v137
	v_mul_f32_e32 v136, v136, v140
	v_mul_f32_e32 v136, v136, v141
	v_sub_f32_e32 v140, 1.0, v137
	v_add_f32_e32 v137, 1.0, v137
	v_mul_f32_e32 v137, v140, v137
	v_max_f32_e32 v137, 0, v137
	v_sqrt_f32_e32 v137, v137
	s_nop 0
	v_mul_f32_e32 v136, v137, v136
	v_cvt_pk_bf16_f32 v137, v140, s0
	v_cvt_pk_bf16_f32 v136, v136, s0
	ds_write_b16 v198, v137 offset:6800
	ds_write_b16 v199, v136 offset:6800
	v_add_f32_e32 v136, v142, v170
	v_add_f32_e32 v137, v138, v171
	v_min_f32_e64 v136, -v136, s93
	v_min_f32_e64 v137, -v137, s93
	v_mul_f32_e32 v136, 0x3fb8aa3b, v136
	v_mul_f32_e32 v137, 0x3fb8aa3b, v137
	v_exp_f32_e32 v136, v136
	v_exp_f32_e32 v137, v137
	v_add_f32_e32 v136, 1.0, v136
	v_add_f32_e32 v137, 1.0, v137
	v_mul_f32_e32 v138, v136, v137
	v_rcp_f32_e32 v138, v138
	v_lshlrev_b32_e32 v140, 16, v232
	v_mul_f32_e32 v137, v137, v138
	v_mul_f32_e32 v137, v205, v137
	v_mul_f32_e32 v137, 0x3fb8aa3b, v137
	v_exp_f32_e32 v137, v137
	v_mul_f32_e32 v136, v136, v138
	v_mul_f32_e32 v136, v136, v140
	v_sub_f32_e32 v138, 1.0, v137
	v_add_f32_e32 v137, 1.0, v137
	v_mul_f32_e32 v137, v138, v137
	v_max_f32_e32 v137, 0, v137
	v_sqrt_f32_e32 v137, v137
	s_nop 0
	v_mul_f32_e32 v136, v137, v136
	v_cvt_pk_bf16_f32 v137, v138, s0
	v_cvt_pk_bf16_f32 v136, v136, s0
	ds_write_b16 v198, v137 offset:7200
	ds_write_b16 v199, v136 offset:7200
	v_add_f32_e32 v136, v143, v170
	v_add_f32_e32 v137, v139, v171
	v_min_f32_e64 v136, -v136, s93
	v_min_f32_e64 v137, -v137, s93
	v_mul_f32_e32 v136, 0x3fb8aa3b, v136
	v_mul_f32_e32 v137, 0x3fb8aa3b, v137
	v_exp_f32_e32 v136, v136
	v_exp_f32_e32 v137, v137
	v_add_f32_e32 v136, 1.0, v136
	v_add_f32_e32 v137, 1.0, v137
	v_mul_f32_e32 v138, v136, v137
	v_rcp_f32_e32 v138, v138
	v_lshlrev_b32_e32 v139, 16, v233
	v_mul_f32_e32 v137, v137, v138
	v_mul_f32_e32 v137, v205, v137
	v_mul_f32_e32 v137, 0x3fb8aa3b, v137
	v_exp_f32_e32 v137, v137
	v_mul_f32_e32 v136, v136, v138
	v_mul_f32_e32 v136, v136, v139
	v_sub_f32_e32 v138, 1.0, v137
	v_add_f32_e32 v137, 1.0, v137
	v_mul_f32_e32 v137, v138, v137
	v_max_f32_e32 v137, 0, v137
	v_sqrt_f32_e32 v137, v137
	s_nop 0
	v_mul_f32_e32 v136, v137, v136
	v_cvt_pk_bf16_f32 v136, v136, s0
	ds_write_b16 v199, v136 offset:7600
	v_cvt_pk_bf16_f32 v137, v138, s0
	ds_write_b16 v198, v137 offset:7600
	v_lshlrev_b32_e32 v137, 16, v234
	s_nop 0
	v_lshlrev_b32_e32 v125, 16, v235
	s_nop 0
	v_lshlrev_b32_e32 v124, 16, v236
	s_nop 0
	v_lshlrev_b32_e32 v123, 16, v237
	v_lshlrev_b32_e32 v123, 16, v238
	s_nop 0
	v_lshlrev_b32_e32 v123, 16, v239
	s_nop 0
	v_lshlrev_b32_e32 v123, 16, v240
	s_nop 0
	v_lshlrev_b32_e32 v123, 16, v241
	s_nop 0
	s_branch .LBB0_847
; #define LAS __attribute__((address_space(3)))
; DI unsigned pk2(float a, float b) { f32x2 v = {a, b}; bf2_t r = __builtin_convertvector(v, bf2_t); return __builtin_bit_cast(unsigned, r); }
; DI void phase_rglru(const Params& p, unsigned char* shm) {
;     ...
;                 for (int u = 0; u < 2; ++u) {
;                     if (u == 1 && w >= 4) break;
;                     f32x4 acc[4][2];
; #pragma unroll
;                     for (int mt = 0; mt < 4; ++mt) { acc[mt][0] = (f32x4){0.f, 0.f, 0.f, 0.f}; acc[mt][1] = (f32x4){0.f, 0.f, 0.f, 0.f}; }
; #pragma unroll
;                     for (int kk = 0; kk < 6; ++kk)
; #pragma unroll
;                         for (int mt = 0; mt < 4; ++mt) {
;                             const bf16x8 af = *(const LAS bf16x8*)(lds + XC + (16 * mt + fr) * TR + (32 * kk + 8 * fq) * 2);
;                             acc[mt][0] = __builtin_amdgcn_mfma_f32_16x16x32_bf16(af, Bf[u][kk], acc[mt][0], 0, 0, 0);
;                             acc[mt][1] = __builtin_amdgcn_mfma_f32_16x16x32_bf16(af, Bf[2 + u][kk], acc[mt][1], 0, 0, 0);
;                         }
;                     const int ch = chb + 16 * u + fr;
;                     const float ba = gb[ch], bx = gb[192 + ch], sp = gb[384 + ch];
; #pragma unroll
;                     for (int mt = 0; mt < 4; ++mt)
; #pragma unroll
;                         for (int j = 0; j < 4; ++j) {
;                             const int t = 16 * mt + 4 * fq + j;
;                             const float ea = 1.f + __expf(fminf(-(acc[mt][0][j] + ba), 40.f)), ex = 1.f + __expf(fminf(-(acc[mt][1][j] + bx), 40.f));
;                             const float inv = __builtin_amdgcn_rcpf(ea * ex);
;                             const float r = inv * ex, ig = inv * ea;
;                             const float av = __expf(r * sp), om = 1.f - av;
;                             const float xcv = __uint_as_float((unsigned)*(const LAS bf16_t*)(lds + XC + t * TR + ch * 2) << 16);
;                             const float bt = __builtin_amdgcn_sqrtf(fmaxf(om * (1.f + av), 0.f)) * (ig * xcv);
;                             *(LAS bf16_t*)(lds + LAo + t * TR + ch * 2) = (bf16_t)(pk2(om, 0.f) & 0xffffu);
;                             *(LAS bf16_t*)(lds + BTo + t * TR + ch * 2) = (bf16_t)(pk2(bt, 0.f) & 0xffffu);
;                         }
.Lgates_b:
	ds_read_b128 v[120:123], v204 offset:39680
	ds_read_b128 v[124:127], v204 offset:46080
	ds_read_b128 v[128:131], v204 offset:39744
	ds_read_b128 v[132:135], v204 offset:46144
	ds_read_b128 v[226:229], v204 offset:39808
	s_waitcnt lgkmcnt(4)
	v_mfma_f32_16x16x32_bf16 v[214:217], v[120:123], v[24:27], 0
	v_mfma_f32_16x16x32_bf16 v[210:213], v[120:123], v[72:75], 0
	ds_read_b128 v[230:233], v204 offset:46208
	s_waitcnt lgkmcnt(4)
	v_mfma_f32_16x16x32_bf16 v[218:221], v[124:127], v[24:27], 0
	v_mfma_f32_16x16x32_bf16 v[222:225], v[124:127], v[72:75], 0
	ds_read_b128 v[120:123], v204 offset:39872
	s_waitcnt lgkmcnt(4)
	v_mfma_f32_16x16x32_bf16 v[214:217], v[128:131], v[28:31], v[214:217]
	v_mfma_f32_16x16x32_bf16 v[210:213], v[128:131], v[76:79], v[210:213]
	ds_read_b128 v[124:127], v204 offset:46272
	s_waitcnt lgkmcnt(4)
	v_mfma_f32_16x16x32_bf16 v[218:221], v[132:135], v[28:31], v[218:221]
	v_mfma_f32_16x16x32_bf16 v[222:225], v[132:135], v[76:79], v[222:225]
	ds_read_b128 v[128:131], v204 offset:39936
	s_waitcnt lgkmcnt(4)
	v_mfma_f32_16x16x32_bf16 v[214:217], v[226:229], v[32:35], v[214:217]
	v_mfma_f32_16x16x32_bf16 v[210:213], v[226:229], v[80:83], v[210:213]
	ds_read_b128 v[132:135], v204 offset:46336
	s_waitcnt lgkmcnt(4)
	v_mfma_f32_16x16x32_bf16 v[218:221], v[230:233], v[32:35], v[218:221]
	v_mfma_f32_16x16x32_bf16 v[222:225], v[230:233], v[80:83], v[222:225]
	s_waitcnt lgkmcnt(3)
	v_mfma_f32_16x16x32_bf16 v[214:217], v[120:123], v[36:39], v[214:217]
	v_mfma_f32_16x16x32_bf16 v[210:213], v[120:123], v[84:87], v[210:213]
	s_waitcnt lgkmcnt(2)
	v_mfma_f32_16x16x32_bf16 v[218:221], v[124:127], v[36:39], v[218:221]
	v_mfma_f32_16x16x32_bf16 v[222:225], v[124:127], v[84:87], v[222:225]
	s_waitcnt lgkmcnt(1)
	v_mfma_f32_16x16x32_bf16 v[214:217], v[128:131], v[40:43], v[214:217]
	v_mfma_f32_16x16x32_bf16 v[210:213], v[128:131], v[88:91], v[210:213]
	s_waitcnt lgkmcnt(0)
	v_mfma_f32_16x16x32_bf16 v[218:221], v[132:135], v[40:43], v[218:221]
	v_mfma_f32_16x16x32_bf16 v[222:225], v[132:135], v[88:91], v[222:225]
	ds_read_b128 v[120:123], v204 offset:40000
	s_nop 1
	ds_read_b128 v[128:131], v204 offset:46400
	ds_read2st64_b32 v[170:171], v185 offset1:3
	ds_read_b32 v205, v185 offset:1536
	ds_read_u16 v226, v197 offset:26880
	ds_read_u16 v227, v197 offset:27280
	ds_read_u16 v228, v197 offset:27680
	ds_read_u16 v229, v197 offset:28080
	ds_read_u16 v230, v197 offset:33280
	ds_read_u16 v231, v197 offset:33680
	ds_read_u16 v232, v197 offset:34080
	ds_read_u16 v233, v197 offset:34480
	ds_read_u16 v234, v197 offset:39680
	ds_read_u16 v235, v197 offset:40080
	ds_read_u16 v236, v197 offset:40480
	ds_read_u16 v237, v197 offset:40880
	ds_read_u16 v238, v197 offset:46080
	ds_read_u16 v239, v197 offset:46480
	ds_read_u16 v240, v197 offset:46880
	ds_read_u16 v241, v197 offset:47280
	s_waitcnt lgkmcnt(15)
	v_mfma_f32_16x16x32_bf16 v[124:127], v[120:123], v[44:47], v[214:217]
	v_mfma_f32_16x16x32_bf16 v[120:123], v[120:123], v[92:95], v[210:213]
	s_waitcnt lgkmcnt(0)
	s_nop 6
	v_lshlrev_b32_e32 v211, 16, v226
	v_lshlrev_b32_e32 v149, 16, v227
	v_lshlrev_b32_e32 v148, 16, v228
	v_lshlrev_b32_e32 v147, 16, v229
	v_add_f32_e32 v124, v124, v170
	v_add_f32_e32 v120, v120, v171
	v_min_f32_e64 v124, -v124, s93
	v_min_f32_e64 v120, -v120, s93
	v_mul_f32_e32 v124, 0x3fb8aa3b, v124
	v_mul_f32_e32 v120, 0x3fb8aa3b, v120
	v_exp_f32_e32 v124, v124
	v_exp_f32_e32 v120, v120
	v_add_f32_e32 v124, 1.0, v124
	v_lshlrev_b32_e32 v145, 16, v230
	v_add_f32_e32 v120, 1.0, v120
	v_lshlrev_b32_e32 v141, 16, v231
	v_add_f32_e32 v121, v121, v171
	v_min_f32_e64 v121, -v121, s93
	v_mul_f32_e32 v121, 0x3fb8aa3b, v121
	v_exp_f32_e32 v121, v121
	v_mfma_f32_16x16x32_bf16 v[132:135], v[128:131], v[44:47], v[218:221]
	v_add_f32_e32 v121, 1.0, v121
	v_lshlrev_b32_e32 v140, 16, v232
	v_mfma_f32_16x16x32_bf16 v[128:131], v[128:131], v[92:95], v[222:225]
	s_nop 0
	v_lshlrev_b32_e32 v139, 16, v233
	s_nop 0
	v_mul_f32_e32 v136, v124, v120
	v_rcp_f32_e32 v136, v136
	s_nop 0
	v_mul_f32_e32 v120, v120, v136
	v_mul_f32_e32 v120, v205, v120
	v_mul_f32_e32 v120, 0x3fb8aa3b, v120
	v_exp_f32_e32 v120, v120
	v_mul_f32_e32 v124, v124, v136
	v_lshlrev_b32_e32 v137, 16, v234
	v_mul_f32_e32 v124, v124, v137
	v_sub_f32_e32 v136, 1.0, v120
	v_add_f32_e32 v120, 1.0, v120
	v_mul_f32_e32 v120, v136, v120
	v_max_f32_e32 v120, 0, v120
	v_sqrt_f32_e32 v120, v120
	s_nop 0
	v_mul_f32_e32 v120, v120, v124
	v_cvt_pk_bf16_f32 v120, v120, s0
	ds_write_b16 v199, v120 offset:12800
	v_add_f32_e32 v120, v125, v170
	v_min_f32_e64 v120, -v120, s93
	v_mul_f32_e32 v120, 0x3fb8aa3b, v120
	v_exp_f32_e32 v120, v120
	v_cvt_pk_bf16_f32 v124, v136, s0
	ds_write_b16 v198, v124 offset:12800
	v_add_f32_e32 v120, 1.0, v120
	v_mul_f32_e32 v124, v120, v121
	v_rcp_f32_e32 v124, v124
	v_lshlrev_b32_e32 v125, 16, v235
	v_mul_f32_e32 v121, v121, v124
	v_mul_f32_e32 v121, v205, v121
	v_mul_f32_e32 v121, 0x3fb8aa3b, v121
	v_exp_f32_e32 v121, v121
	v_mul_f32_e32 v120, v120, v124
	v_mul_f32_e32 v120, v120, v125
	v_sub_f32_e32 v124, 1.0, v121
	v_add_f32_e32 v121, 1.0, v121
	v_mul_f32_e32 v121, v124, v121
	v_max_f32_e32 v121, 0, v121
	v_sqrt_f32_e32 v121, v121
	s_nop 0
	v_mul_f32_e32 v120, v121, v120
	v_cvt_pk_bf16_f32 v121, v124, s0
	v_cvt_pk_bf16_f32 v120, v120, s0
	ds_write_b16 v198, v121 offset:13200
	ds_write_b16 v199, v120 offset:13200
	v_add_f32_e32 v120, v126, v170
	v_add_f32_e32 v121, v122, v171
	v_min_f32_e64 v120, -v120, s93
	v_min_f32_e64 v121, -v121, s93
; #define LAS __attribute__((address_space(3)))
; DI unsigned pk2(float a, float b) { f32x2 v = {a, b}; bf2_t r = __builtin_convertvector(v, bf2_t); return __builtin_bit_cast(unsigned, r); }
; DI void phase_rglru(const Params& p, unsigned char* shm) {
;     ...
;                     const int ch = chb + 16 * u + fr;
;                     const float ba = gb[ch], bx = gb[192 + ch], sp = gb[384 + ch];
; #pragma unroll
;                     for (int mt = 0; mt < 4; ++mt)
; #pragma unroll
;                         for (int j = 0; j < 4; ++j) {
;                             const int t = 16 * mt + 4 * fq + j;
;                             const float ea = 1.f + __expf(fminf(-(acc[mt][0][j] + ba), 40.f)), ex = 1.f + __expf(fminf(-(acc[mt][1][j] + bx), 40.f));
;                             const float inv = __builtin_amdgcn_rcpf(ea * ex);
;                             const float r = inv * ex, ig = inv * ea;
;                             const float av = __expf(r * sp), om = 1.f - av;
;                             const float xcv = __uint_as_float((unsigned)*(const LAS bf16_t*)(lds + XC + t * TR + ch * 2) << 16);
;                             const float bt = __builtin_amdgcn_sqrtf(fmaxf(om * (1.f + av), 0.f)) * (ig * xcv);
;                             *(LAS bf16_t*)(lds + LAo + t * TR + ch * 2) = (bf16_t)(pk2(om, 0.f) & 0xffffu);
;                             *(LAS bf16_t*)(lds + BTo + t * TR + ch * 2) = (bf16_t)(pk2(bt, 0.f) & 0xffffu);
;                         }
	v_mul_f32_e32 v120, 0x3fb8aa3b, v120
	v_mul_f32_e32 v121, 0x3fb8aa3b, v121
	v_exp_f32_e32 v120, v120
	v_exp_f32_e32 v121, v121
	v_add_f32_e32 v120, 1.0, v120
	v_add_f32_e32 v121, 1.0, v121
	v_mul_f32_e32 v122, v120, v121
	v_rcp_f32_e32 v122, v122
	v_lshlrev_b32_e32 v124, 16, v236
	v_mul_f32_e32 v121, v121, v122
	v_mul_f32_e32 v121, v205, v121
	v_mul_f32_e32 v121, 0x3fb8aa3b, v121
	v_exp_f32_e32 v121, v121
	v_mul_f32_e32 v120, v120, v122
	v_mul_f32_e32 v120, v120, v124
	v_sub_f32_e32 v122, 1.0, v121
	v_add_f32_e32 v121, 1.0, v121
	v_mul_f32_e32 v121, v122, v121
	v_max_f32_e32 v121, 0, v121
	v_sqrt_f32_e32 v121, v121
	s_nop 0
	v_mul_f32_e32 v120, v121, v120
	v_cvt_pk_bf16_f32 v121, v122, s0
	v_cvt_pk_bf16_f32 v120, v120, s0
	ds_write_b16 v198, v121 offset:13600
	ds_write_b16 v199, v120 offset:13600
	v_add_f32_e32 v120, v127, v170
	v_add_f32_e32 v121, v123, v171
	v_min_f32_e64 v120, -v120, s93
	v_min_f32_e64 v121, -v121, s93
	v_mul_f32_e32 v120, 0x3fb8aa3b, v120
	v_mul_f32_e32 v121, 0x3fb8aa3b, v121
	v_exp_f32_e32 v120, v120
	v_exp_f32_e32 v121, v121
	v_add_f32_e32 v120, 1.0, v120
	v_add_f32_e32 v121, 1.0, v121
	v_mul_f32_e32 v122, v120, v121
	v_rcp_f32_e32 v122, v122
	v_lshlrev_b32_e32 v123, 16, v237
	v_mul_f32_e32 v121, v121, v122
	v_mul_f32_e32 v121, v205, v121
	v_mul_f32_e32 v121, 0x3fb8aa3b, v121
	v_exp_f32_e32 v121, v121
	v_mul_f32_e32 v120, v120, v122
	v_mul_f32_e32 v120, v120, v123
	v_sub_f32_e32 v122, 1.0, v121
	v_add_f32_e32 v121, 1.0, v121
	v_mul_f32_e32 v121, v122, v121
	v_max_f32_e32 v121, 0, v121
	v_sqrt_f32_e32 v121, v121
	v_lshlrev_b32_e32 v123, 16, v238
	v_mul_f32_e32 v120, v121, v120
	v_cvt_pk_bf16_f32 v121, v122, s0
	v_cvt_pk_bf16_f32 v120, v120, s0
	ds_write_b16 v198, v121 offset:14000
	ds_write_b16 v199, v120 offset:14000
	v_add_f32_e32 v120, v132, v170
	v_add_f32_e32 v121, v128, v171
	v_min_f32_e64 v120, -v120, s93
	v_min_f32_e64 v121, -v121, s93
	v_mul_f32_e32 v120, 0x3fb8aa3b, v120
	v_mul_f32_e32 v121, 0x3fb8aa3b, v121
	v_exp_f32_e32 v120, v120
	v_exp_f32_e32 v121, v121
	v_add_f32_e32 v120, 1.0, v120
	v_add_f32_e32 v121, 1.0, v121
	v_mul_f32_e32 v122, v120, v121
	v_rcp_f32_e32 v122, v122
	s_nop 0
	v_mul_f32_e32 v121, v121, v122
	v_mul_f32_e32 v121, v205, v121
	v_mul_f32_e32 v121, 0x3fb8aa3b, v121
	v_exp_f32_e32 v121, v121
	v_mul_f32_e32 v120, v120, v122
	v_mul_f32_e32 v120, v120, v123
	v_sub_f32_e32 v122, 1.0, v121
	v_add_f32_e32 v121, 1.0, v121
	v_mul_f32_e32 v121, v122, v121
	v_max_f32_e32 v121, 0, v121
	v_sqrt_f32_e32 v121, v121
	v_lshlrev_b32_e32 v123, 16, v239
	v_mul_f32_e32 v120, v121, v120
	v_cvt_pk_bf16_f32 v121, v122, s0
	v_cvt_pk_bf16_f32 v120, v120, s0
	ds_write_b16 v198, v121 offset:19200
	ds_write_b16 v199, v120 offset:19200
	v_add_f32_e32 v120, v133, v170
	v_add_f32_e32 v121, v129, v171
	v_min_f32_e64 v120, -v120, s93
	v_min_f32_e64 v121, -v121, s93
	v_mul_f32_e32 v120, 0x3fb8aa3b, v120
	v_mul_f32_e32 v121, 0x3fb8aa3b, v121
	v_exp_f32_e32 v120, v120
	v_exp_f32_e32 v121, v121
	v_add_f32_e32 v120, 1.0, v120
	v_add_f32_e32 v121, 1.0, v121
	v_mul_f32_e32 v122, v120, v121
	v_rcp_f32_e32 v122, v122
	s_nop 0
	v_mul_f32_e32 v121, v121, v122
	v_mul_f32_e32 v121, v205, v121
	v_mul_f32_e32 v121, 0x3fb8aa3b, v121
	v_exp_f32_e32 v121, v121
	v_mul_f32_e32 v120, v120, v122
	v_mul_f32_e32 v120, v120, v123
	v_sub_f32_e32 v122, 1.0, v121
	v_add_f32_e32 v121, 1.0, v121
	v_mul_f32_e32 v121, v122, v121
	v_max_f32_e32 v121, 0, v121
	v_sqrt_f32_e32 v121, v121
	v_lshlrev_b32_e32 v123, 16, v240
	v_mul_f32_e32 v120, v121, v120
	v_cvt_pk_bf16_f32 v121, v122, s0
	v_cvt_pk_bf16_f32 v120, v120, s0
	ds_write_b16 v198, v121 offset:19600
	ds_write_b16 v199, v120 offset:19600
	v_add_f32_e32 v120, v134, v170
	v_add_f32_e32 v121, v130, v171
	v_min_f32_e64 v120, -v120, s93
	v_min_f32_e64 v121, -v121, s93
	v_mul_f32_e32 v120, 0x3fb8aa3b, v120
	v_mul_f32_e32 v121, 0x3fb8aa3b, v121
	v_exp_f32_e32 v120, v120
	v_exp_f32_e32 v121, v121
	v_add_f32_e32 v120, 1.0, v120
	v_add_f32_e32 v121, 1.0, v121
	v_mul_f32_e32 v122, v120, v121
	v_rcp_f32_e32 v122, v122
	s_nop 0
	v_mul_f32_e32 v121, v121, v122
	v_mul_f32_e32 v121, v205, v121
	v_mul_f32_e32 v121, 0x3fb8aa3b, v121
	v_exp_f32_e32 v121, v121
	v_mul_f32_e32 v120, v120, v122
	v_mul_f32_e32 v120, v120, v123
	v_sub_f32_e32 v122, 1.0, v121
	v_add_f32_e32 v121, 1.0, v121
	v_mul_f32_e32 v121, v122, v121
	v_max_f32_e32 v121, 0, v121
	v_sqrt_f32_e32 v121, v121
	v_lshlrev_b32_e32 v123, 16, v241
	v_mul_f32_e32 v120, v121, v120
	v_cvt_pk_bf16_f32 v121, v122, s0
	v_cvt_pk_bf16_f32 v120, v120, s0
	ds_write_b16 v198, v121 offset:20000
	ds_write_b16 v199, v120 offset:20000
	v_add_f32_e32 v120, v135, v170
	v_add_f32_e32 v121, v131, v171
	v_min_f32_e64 v120, -v120, s93
	v_min_f32_e64 v121, -v121, s93
	v_mul_f32_e32 v120, 0x3fb8aa3b, v120
	v_mul_f32_e32 v121, 0x3fb8aa3b, v121
	v_exp_f32_e32 v120, v120
	v_exp_f32_e32 v121, v121
	v_add_f32_e32 v120, 1.0, v120
	v_add_f32_e32 v121, 1.0, v121
	v_mul_f32_e32 v122, v120, v121
	v_rcp_f32_e32 v122, v122
	s_nop 0
	v_mul_f32_e32 v121, v121, v122
	v_mul_f32_e32 v121, v205, v121
	v_mul_f32_e32 v121, 0x3fb8aa3b, v121
	v_mul_f32_e32 v120, v120, v122
	v_exp_f32_e32 v122, v121
	v_mul_f32_e32 v120, v120, v123
	v_sub_f32_e32 v121, 1.0, v122
	v_add_f32_e32 v122, 1.0, v122
	v_mul_f32_e32 v122, v121, v122
	v_max_f32_e32 v122, 0, v122
	v_sqrt_f32_e32 v122, v122
	v_cvt_pk_bf16_f32 v121, v121, s0
	ds_write_b16 v198, v121 offset:20400
	v_mul_f32_e32 v120, v122, v120
	v_cvt_pk_bf16_f32 v120, v120, s0
	ds_write_b16 v199, v120 offset:20400
